# v27
# speedup vs baseline: 1.0305x; 1.0068x over previous
.LBB0_69:
	s_add_i32 s4, s4, 1
	s_cmp_lg_u32 s4, 16
	s_cselect_b32 s4, s4, 0
	s_add_i32 s6, s5, 0x8000
	s_and_b32 s5, s5, 0x8000
	s_lshl_b32 s8, s4, 6
	s_and_b32 s7, s6, 0x8000
	v_lshl_or_b32 v95, v93, 1, s5
	v_or_b32_e32 v94, s8, v90
	v_add_u32_e32 v96, s7, v89
	s_ashr_i32 s9, s8, 31
	v_add_u32_e32 v118, v95, v64
	v_add_u32_e32 v114, v95, v92
	v_ashrrev_i32_e32 v95, 31, v94
	v_readfirstlane_b32 s7, v96
	v_add_u32_e32 v97, 0x400, v96
	v_add_u32_e32 v98, 0x800, v96
	v_add_u32_e32 v99, 0xc00, v96
	v_add_u32_e32 v100, 0x4000, v96
	s_lshl_b64 s[8:9], s[8:9], 1
	v_add_u32_e32 v101, 0x4400, v96
	v_add_u32_e32 v102, 0x4800, v96
	v_add_u32_e32 v104, 0x4c00, v96
	v_lshlrev_b64 v[94:95], 1, v[94:95]
	v_readfirstlane_b32 s36, v97
	v_readfirstlane_b32 s37, v98
	v_readfirstlane_b32 s72, v99
	v_lshl_add_u64 v[96:97], v[74:75], 0, s[8:9]
	v_readfirstlane_b32 s73, v100
	v_lshl_add_u64 v[98:99], v[76:77], 0, s[8:9]
	v_readfirstlane_b32 s85, v101
	v_lshl_add_u64 v[100:101], v[78:79], 0, s[8:9]
	v_readfirstlane_b32 s86, v102
	v_lshl_add_u64 v[102:103], v[80:81], 0, s[8:9]
	v_readfirstlane_b32 s8, v104
	v_lshl_add_u64 v[104:105], v[66:67], 0, v[94:95]
	s_mov_b32 m0, s7
	s_waitcnt vmcnt(0) lgkmcnt(0)
	s_barrier
	v_lshl_add_u64 v[106:107], v[68:69], 0, v[94:95]
	global_load_lds_dwordx4 v[104:105], off
	s_mov_b32 m0, s36
	v_lshl_add_u64 v[108:109], v[70:71], 0, v[94:95]
	global_load_lds_dwordx4 v[106:107], off
	s_mov_b32 m0, s37
	v_lshl_add_u64 v[94:95], v[72:73], 0, v[94:95]
	global_load_lds_dwordx4 v[108:109], off
	s_mov_b32 m0, s72
	s_cmp_eq_u32 s6, 0x78000
	global_load_lds_dwordx4 v[94:95], off
	s_mov_b32 m0, s73
	s_nop 0
	global_load_lds_dwordx4 v[96:97], off
	s_mov_b32 m0, s85
	s_nop 0
	global_load_lds_dwordx4 v[98:99], off
	s_mov_b32 m0, s86
	s_nop 0
	global_load_lds_dwordx4 v[100:101], off
	s_mov_b32 m0, s8
	s_nop 0
	global_load_lds_dwordx4 v[102:103], off
	s_setprio 1
	ds_read_b128 v[94:97], v114 offset:16384
	ds_read_b128 v[98:101], v114 offset:18432
	ds_read_b128 v[102:105], v118
	ds_read_b128 v[106:109], v118 offset:2048
	ds_read_b128 v[110:113], v114 offset:20480
	ds_read_b128 v[114:117], v114 offset:22528
	s_waitcnt lgkmcnt(0)
	v_mfma_f32_16x16x32_bf16 v[60:63], v[94:97], v[102:105], v[60:63]
	v_mfma_f32_16x16x32_bf16 v[56:59], v[98:101], v[102:105], v[56:59]
	v_mfma_f32_16x16x32_bf16 v[52:55], v[110:113], v[102:105], v[52:55]
	v_mfma_f32_16x16x32_bf16 v[40:43], v[114:117], v[102:105], v[40:43]
	v_mfma_f32_16x16x32_bf16 v[32:35], v[94:97], v[106:109], v[32:35]
	v_mfma_f32_16x16x32_bf16 v[28:31], v[98:101], v[106:109], v[28:31]
	v_mfma_f32_16x16x32_bf16 v[24:27], v[110:113], v[106:109], v[24:27]
	v_mfma_f32_16x16x32_bf16 v[20:23], v[114:117], v[106:109], v[20:23]
	ds_read_b128 v[102:105], v118 offset:4096
	ds_read_b128 v[106:109], v118 offset:6144
	s_waitcnt lgkmcnt(1)
	v_mfma_f32_16x16x32_bf16 v[12:15], v[94:97], v[102:105], v[12:15]
	s_waitcnt lgkmcnt(0)
	v_mfma_f32_16x16x32_bf16 v[44:47], v[94:97], v[106:109], v[44:47]
	v_lshl_or_b32 v94, v91, 1, s5
	v_add_u32_e32 v118, v94, v64
	v_add_u32_e32 v119, v94, v92
	v_mfma_f32_16x16x32_bf16 v[8:11], v[98:101], v[102:105], v[8:11]
	s_mov_b32 s5, s6
	v_mfma_f32_16x16x32_bf16 v[4:7], v[110:113], v[102:105], v[4:7]
	v_mfma_f32_16x16x32_bf16 v[0:3], v[114:117], v[102:105], v[0:3]
	v_mfma_f32_16x16x32_bf16 v[48:51], v[98:101], v[106:109], v[48:51]
	ds_read_b128 v[94:97], v119 offset:16384
	ds_read_b128 v[98:101], v119 offset:18432
	v_mfma_f32_16x16x32_bf16 v[36:39], v[110:113], v[106:109], v[36:39]
	v_mfma_f32_16x16x32_bf16 v[16:19], v[114:117], v[106:109], v[16:19]
	ds_read_b128 v[102:105], v118
	ds_read_b128 v[106:109], v118 offset:2048
	ds_read_b128 v[110:113], v119 offset:20480
	ds_read_b128 v[114:117], v119 offset:22528
	s_waitcnt lgkmcnt(3)
	v_mfma_f32_16x16x32_bf16 v[60:63], v[94:97], v[102:105], v[60:63]
	v_mfma_f32_16x16x32_bf16 v[56:59], v[98:101], v[102:105], v[56:59]
	s_waitcnt lgkmcnt(1)
	v_mfma_f32_16x16x32_bf16 v[52:55], v[110:113], v[102:105], v[52:55]
	s_waitcnt lgkmcnt(0)
	v_mfma_f32_16x16x32_bf16 v[40:43], v[114:117], v[102:105], v[40:43]
	v_mfma_f32_16x16x32_bf16 v[32:35], v[94:97], v[106:109], v[32:35]
	v_mfma_f32_16x16x32_bf16 v[28:31], v[98:101], v[106:109], v[28:31]
	v_mfma_f32_16x16x32_bf16 v[24:27], v[110:113], v[106:109], v[24:27]
	v_mfma_f32_16x16x32_bf16 v[20:23], v[114:117], v[106:109], v[20:23]
	ds_read_b128 v[102:105], v118 offset:4096
	ds_read_b128 v[106:109], v118 offset:6144
	s_waitcnt lgkmcnt(1)
	v_mfma_f32_16x16x32_bf16 v[12:15], v[94:97], v[102:105], v[12:15]
	v_mfma_f32_16x16x32_bf16 v[8:11], v[98:101], v[102:105], v[8:11]
	v_mfma_f32_16x16x32_bf16 v[4:7], v[110:113], v[102:105], v[4:7]
	v_mfma_f32_16x16x32_bf16 v[0:3], v[114:117], v[102:105], v[0:3]
	s_waitcnt lgkmcnt(0)
	v_mfma_f32_16x16x32_bf16 v[44:47], v[94:97], v[106:109], v[44:47]
	v_mfma_f32_16x16x32_bf16 v[48:51], v[98:101], v[106:109], v[48:51]
	v_mfma_f32_16x16x32_bf16 v[36:39], v[110:113], v[106:109], v[36:39]
	v_mfma_f32_16x16x32_bf16 v[16:19], v[114:117], v[106:109], v[16:19]
	s_setprio 0
	s_cbranch_scc0 .LBB0_69
	v_lshlrev_b32_e32 v70, 1, v93
	v_add_u32_e32 v89, v70, v92
	s_waitcnt vmcnt(0)
	s_barrier
	ds_read_b128 v[66:69], v89 offset:49152
	ds_read_b128 v[74:77], v89 offset:51200
	ds_read_b128 v[78:81], v89 offset:53248
	ds_read_b128 v[94:97], v89 offset:55296
	v_add_u32_e32 v90, v70, v64
	ds_read_b128 v[70:73], v90 offset:32768
	s_waitcnt lgkmcnt(0)
	v_mfma_f32_16x16x32_bf16 v[60:63], v[66:69], v[70:73], v[60:63]
	v_lshlrev_b32_e32 v89, 1, v91
	v_add_u32_e32 v106, v89, v92
	v_add_u32_e32 v64, v89, v64
	v_mfma_f32_16x16x32_bf16 v[56:59], v[74:77], v[70:73], v[56:59]
	s_cmp_lt_i32 s34, 5
	s_mov_b32 s72, 0
	v_mfma_f32_16x16x32_bf16 v[52:55], v[78:81], v[70:73], v[52:55]
	v_mfma_f32_16x16x32_bf16 v[40:43], v[94:97], v[70:73], v[40:43]
	ds_read_b128 v[70:73], v90 offset:34816
	s_waitcnt lgkmcnt(0)
	v_mfma_f32_16x16x32_bf16 v[32:35], v[66:69], v[70:73], v[32:35]
	v_mfma_f32_16x16x32_bf16 v[28:31], v[74:77], v[70:73], v[28:31]
	v_mfma_f32_16x16x32_bf16 v[24:27], v[78:81], v[70:73], v[24:27]
	v_mfma_f32_16x16x32_bf16 v[20:23], v[94:97], v[70:73], v[20:23]
	ds_read_b128 v[70:73], v90 offset:36864
	s_waitcnt lgkmcnt(0)
	v_mfma_f32_16x16x32_bf16 v[12:15], v[66:69], v[70:73], v[12:15]
	v_mfma_f32_16x16x32_bf16 v[8:11], v[74:77], v[70:73], v[8:11]
	v_mfma_f32_16x16x32_bf16 v[4:7], v[78:81], v[70:73], v[4:7]
	v_mfma_f32_16x16x32_bf16 v[0:3], v[94:97], v[70:73], v[0:3]
	ds_read_b128 v[70:73], v90 offset:38912
	s_waitcnt lgkmcnt(0)
	v_mfma_f32_16x16x32_bf16 v[44:47], v[66:69], v[70:73], v[44:47]
	ds_read_b128 v[66:69], v106 offset:55296
	ds_read_b128 v[90:93], v106 offset:53248
	v_mfma_f32_16x16x32_bf16 v[48:51], v[74:77], v[70:73], v[48:51]
	ds_read_b128 v[74:77], v64 offset:38912
	ds_read_b128 v[98:101], v64 offset:36864
	ds_read_b128 v[102:105], v106 offset:51200
	ds_read_b128 v[106:109], v106 offset:49152
	v_mfma_f32_16x16x32_bf16 v[36:39], v[78:81], v[70:73], v[36:39]
	ds_read_b128 v[78:81], v64 offset:34816
	ds_read_b128 v[110:113], v64 offset:32768
	v_lshlrev_b32_e32 v64, 6, v88
	s_waitcnt lgkmcnt(0)
	v_mfma_f32_16x16x32_bf16 v[16:19], v[94:97], v[70:73], v[16:19]
	v_add_u32_e32 v70, s71, v64
	v_or_b32_e32 v70, v70, v86
	v_ashrrev_i32_e32 v71, 31, v70
	v_lshl_add_u64 v[70:71], v[70:71], 2, s[24:25]
	s_barrier
	global_load_dword v72, v[70:71], off
	global_load_dword v73, v[70:71], off offset:64
	global_load_dword v88, v[70:71], off offset:128
	s_nop 0
	global_load_dword v70, v[70:71], off offset:192
	v_and_b32_e32 v71, 48, v85
	v_or_b32_e32 v89, v64, v86
	v_lshl_or_b32 v64, v87, 8, v71
	v_mfma_f32_16x16x32_bf16 v[40:43], v[66:69], v[110:113], v[40:43]
	s_barrier
	v_mfma_f32_16x16x32_bf16 v[32:35], v[106:109], v[78:81], v[32:35]
	s_waitcnt vmcnt(3)
	v_fmamk_f32 v71, v72, 0x3a800000, v83
	s_waitcnt vmcnt(2)
	v_fmamk_f32 v72, v73, 0x3a800000, v83
	v_mul_f32_e32 v87, 0x4b800000, v71
	v_cmp_gt_f32_e32 vcc, s38, v71
	s_waitcnt vmcnt(1)
	v_fmamk_f32 v73, v88, 0x3a800000, v83
	v_mul_f32_e32 v88, 0x4b800000, v72
	v_cndmask_b32_e32 v71, v71, v87, vcc
	v_cmp_gt_f32_e64 s[4:5], s38, v72
	v_rsq_f32_e32 v71, v71
	s_waitcnt vmcnt(0)
	v_fmamk_f32 v70, v70, 0x3a800000, v83
	v_cndmask_b32_e64 v72, v72, v88, s[4:5]
	v_mul_f32_e32 v94, 0x4b800000, v73
	v_cmp_gt_f32_e64 s[6:7], s38, v73
	v_rsq_f32_e32 v72, v72
	v_mul_f32_e32 v95, 0x4b800000, v70
	v_cndmask_b32_e64 v73, v73, v94, s[6:7]
	v_cmp_gt_f32_e64 s[8:9], s38, v70
	v_rsq_f32_e32 v73, v73
	v_mfma_f32_16x16x32_bf16 v[28:31], v[102:105], v[78:81], v[28:31]
	v_cndmask_b32_e64 v70, v70, v95, s[8:9]
	v_rsq_f32_e32 v87, v70
	v_mul_f32_e32 v70, 0x45800000, v71
	v_mul_f32_e32 v88, 0x45800000, v72
	v_cndmask_b32_e32 v70, v71, v70, vcc
	v_mfma_f32_16x16x32_bf16 v[24:27], v[90:93], v[78:81], v[24:27]
	v_cndmask_b32_e64 v72, v72, v88, s[4:5]
	v_pk_mul_f32 v[42:43], v[42:43], v[70:71] op_sel_hi:[1,0]
	v_pk_mul_f32 v[40:41], v[40:41], v[70:71] op_sel_hi:[1,0]
	v_mfma_f32_16x16x32_bf16 v[20:23], v[66:69], v[78:81], v[20:23]
	v_mad_u64_u32 v[78:79], s[4:5], v89, s39, v[64:65]
	ds_write_b128 v78, v[40:43] offset:192
	v_mfma_f32_16x16x32_bf16 v[0:3], v[66:69], v[98:101], v[0:3]
	v_mul_f32_e64 v34, v34, v72
	v_mul_f32_e64 v35, v35, v72
	v_pk_mul_f32 v[32:33], v[32:33], v[72:73] op_sel_hi:[1,0]
	v_mul_f32_e32 v94, 0x45800000, v73
	v_mfma_f32_16x16x32_bf16 v[40:43], v[106:109], v[74:77], v[44:47]
	ds_write_b128 v78, v[32:35] offset:8448
	v_pk_mul_f32 v[30:31], v[30:31], v[72:73] op_sel_hi:[1,0]
	v_pk_mul_f32 v[28:29], v[28:29], v[72:73] op_sel_hi:[1,0]
	v_mfma_f32_16x16x32_bf16 v[32:35], v[102:105], v[74:77], v[48:51]
	v_mul_f32_e32 v95, 0x45800000, v87
	v_cndmask_b32_e64 v88, v73, v94, s[6:7]
	ds_write_b128 v78, v[28:31] offset:8512
	v_mfma_f32_16x16x32_bf16 v[28:31], v[90:93], v[74:77], v[36:39]
	v_cndmask_b32_e64 v94, v87, v95, s[8:9]
	v_pk_mul_f32 v[2:3], v[2:3], v[88:89] op_sel_hi:[1,0]
	v_pk_mul_f32 v[0:1], v[0:1], v[88:89] op_sel_hi:[1,0]
	v_mfma_f32_16x16x32_bf16 v[16:19], v[66:69], v[74:77], v[16:19]
	ds_write_b128 v78, v[0:3] offset:17088
	v_pk_mul_f32 v[2:3], v[42:43], v[94:95] op_sel_hi:[1,0]
	v_pk_mul_f32 v[0:1], v[40:41], v[94:95] op_sel_hi:[1,0]
	v_mfma_f32_16x16x32_bf16 v[8:11], v[102:105], v[98:101], v[8:11]
	ds_write_b128 v78, v[0:3] offset:25344
	v_pk_mul_f32 v[2:3], v[34:35], v[94:95] op_sel_hi:[1,0]
	v_pk_mul_f32 v[0:1], v[32:33], v[94:95] op_sel_hi:[1,0]
	v_mfma_f32_16x16x32_bf16 v[60:63], v[106:109], v[110:113], v[60:63]
	ds_write_b128 v78, v[0:3] offset:25408
	v_pk_mul_f32 v[2:3], v[30:31], v[94:95] op_sel_hi:[1,0]
	v_pk_mul_f32 v[0:1], v[28:29], v[94:95] op_sel_hi:[1,0]
	v_mfma_f32_16x16x32_bf16 v[56:59], v[102:105], v[110:113], v[56:59]
	ds_write_b128 v78, v[0:3] offset:25472
	v_pk_mul_f32 v[2:3], v[18:19], v[94:95] op_sel_hi:[1,0]
	v_pk_mul_f32 v[0:1], v[16:17], v[94:95] op_sel_hi:[1,0]
	v_mfma_f32_16x16x32_bf16 v[52:55], v[90:93], v[110:113], v[52:55]
	s_cselect_b64 s[8:9], -1, 0
	s_cmp_gt_i32 s34, 2
	ds_write_b128 v78, v[0:3] offset:25536
	v_mfma_f32_16x16x32_bf16 v[12:15], v[106:109], v[98:101], v[12:15]
	v_lshl_or_b32 v0, v86, 3, s35
	s_cselect_b32 s34, s51, 0x60000
	v_pk_mul_f32 v[10:11], v[10:11], v[88:89] op_sel_hi:[1,0]
	v_mfma_f32_16x16x32_bf16 v[4:7], v[90:93], v[98:101], v[4:7]
	v_mul_f32_e64 v8, v8, v88
	v_mul_f32_e64 v9, v9, v88
	v_ashrrev_i32_e32 v1, 31, v0
	s_add_u32 s34, s24, s34
	v_pk_mul_f32 v[62:63], v[62:63], v[70:71] op_sel_hi:[1,0]
	v_pk_mul_f32 v[60:61], v[60:61], v[70:71] op_sel_hi:[1,0]
	v_pk_mul_f32 v[58:59], v[58:59], v[70:71] op_sel_hi:[1,0]
	v_pk_mul_f32 v[56:57], v[56:57], v[70:71] op_sel_hi:[1,0]
	v_pk_mul_f32 v[54:55], v[54:55], v[70:71] op_sel_hi:[1,0]
	v_pk_mul_f32 v[52:53], v[52:53], v[70:71] op_sel_hi:[1,0]
	v_pk_mul_f32 v[26:27], v[26:27], v[72:73] op_sel_hi:[1,0]
	v_pk_mul_f32 v[24:25], v[24:25], v[72:73] op_sel_hi:[1,0]
	v_pk_mul_f32 v[22:23], v[22:23], v[72:73] op_sel_hi:[1,0]
	v_pk_mul_f32 v[20:21], v[20:21], v[72:73] op_sel_hi:[1,0]
	v_pk_mul_f32 v[14:15], v[14:15], v[88:89] op_sel_hi:[1,0]
	v_pk_mul_f32 v[12:13], v[12:13], v[88:89] op_sel_hi:[1,0]
	ds_write_b128 v78, v[8:11] offset:16960
	v_pk_mul_f32 v[6:7], v[6:7], v[88:89] op_sel_hi:[1,0]
	v_pk_mul_f32 v[4:5], v[4:5], v[88:89] op_sel_hi:[1,0]
	v_lshlrev_b32_e32 v8, 5, v86
	v_cmp_gt_i32_e64 s[4:5], s50, v0
	v_cmp_eq_u32_e64 s[6:7], 0, v86
	v_lshl_add_u64 v[10:11], v[0:1], 1, s[80:81]
	s_addc_u32 s35, s25, 0
	ds_write_b128 v78, v[60:63]
	ds_write_b128 v78, v[56:59] offset:64
	ds_write_b128 v78, v[52:55] offset:128
	ds_write_b128 v78, v[24:27] offset:8576
	ds_write_b128 v78, v[20:23] offset:8640
	ds_write_b128 v78, v[12:15] offset:16896
	ds_write_b128 v78, v[4:7] offset:17024
	s_waitcnt lgkmcnt(0)
	s_barrier
	s_branch .LBB0_73

.LBB0_90:
	s_ashr_i32 s4, s39, 31
	s_lshr_b32 s4, s4, 29
	s_add_i32 s50, s39, s4
	s_and_b32 s4, s50, -8
	s_or_b32 s5, s4, s33
	s_sub_i32 s51, s39, s4
	s_lshl_b32 s4, s5, 7
	s_mul_i32 s5, s5, 5
	s_mul_i32 s57, s51, 3
	s_add_i32 s5, s5, s57
	s_mul_hi_i32 s57, s5, 0x2aaaaaab
	s_lshr_b32 s65, s57, 31
	v_mov_b32_e32 v17, v138
	s_add_i32 s57, s57, s65
	s_mul_i32 s57, s57, 6
	v_bfe_u32 v1, v17, 3, 3
	v_ashrrev_i32_e32 v0, 6, v17
	v_bitop3_b32 v12, v1, v17, 7 bitop3:0x78
	s_sub_i32 s5, s5, s57
	s_lshl_b32 s72, s5, 6
	v_lshl_or_b32 v10, v0, 5, v1
	v_lshlrev_b32_e32 v16, 3, v12
	v_lshlrev_b32_e32 v23, 12, v0
	v_add_u32_e32 v0, s4, v10
	v_or_b32_e32 v2, s72, v16
	v_mad_i64_i32 v[0:1], s[86:87], v0, s15, v[24:25]
	v_ashrrev_i32_e32 v3, 31, v2
	v_lshlrev_b64 v[8:9], 1, v[2:3]
	v_readfirstlane_b32 s86, v23
	v_lshl_add_u64 v[2:3], v[0:1], 0, v[8:9]
	s_mov_b32 m0, s86
	v_or_b32_e32 v13, 8, v10
	global_load_lds_dwordx4 v[2:3], off
	v_add_u32_e32 v2, s4, v13
	v_or_b32_e32 v6, 0x400, v23
	v_mad_i64_i32 v[2:3], s[88:89], v2, s15, v[24:25]
	v_readfirstlane_b32 s87, v6
	v_lshl_add_u64 v[4:5], v[2:3], 0, v[8:9]
	s_mov_b32 m0, s87
	v_or_b32_e32 v14, 16, v10
	global_load_lds_dwordx4 v[4:5], off
	v_add_u32_e32 v4, s4, v14
	v_mad_i64_i32 v[4:5], s[88:89], v4, s15, v[24:25]
	v_or_b32_e32 v11, 0x800, v23
	v_lshl_add_u64 v[6:7], v[4:5], 0, v[8:9]
	v_readfirstlane_b32 s88, v11
	s_mov_b32 m0, s88
	v_or_b32_e32 v15, 24, v10
	global_load_lds_dwordx4 v[6:7], off
	v_add_u32_e32 v6, s4, v15
	v_or_b32_e32 v11, 0xc00, v23
	v_mad_i64_i32 v[6:7], s[90:91], v6, s15, v[24:25]
	v_readfirstlane_b32 s89, v11
	s_lshl_b32 s8, s51, 7
	v_lshl_add_u64 v[8:9], v[6:7], 0, v[8:9]
	s_mov_b32 m0, s89
	s_ashr_i32 s73, s72, 31
	global_load_lds_dwordx4 v[8:9], off
	v_add_u32_e32 v8, s8, v10
	v_add_u32_e32 v18, 0x4000, v23
	v_mad_i64_i32 v[8:9], s[90:91], v8, s14, v[26:27]
	s_lshl_b64 s[72:73], s[72:73], 1
	v_lshl_add_u64 v[10:11], v[8:9], 0, s[72:73]
	v_lshlrev_b32_e32 v28, 4, v12
	v_readfirstlane_b32 s90, v18
	v_lshl_add_u64 v[10:11], v[10:11], 0, v[28:29]
	s_mov_b32 m0, s90
	v_add_u32_e32 v18, 0x4400, v23
	global_load_lds_dwordx4 v[10:11], off
	v_add_u32_e32 v10, s8, v13
	v_mad_i64_i32 v[10:11], s[92:93], v10, s14, v[26:27]
	v_lshl_add_u64 v[12:13], v[10:11], 0, s[72:73]
	v_readfirstlane_b32 s91, v18
	v_lshl_add_u64 v[12:13], v[12:13], 0, v[28:29]
	s_mov_b32 m0, s91
	s_add_i32 s5, s5, 1
	global_load_lds_dwordx4 v[12:13], off
	v_add_u32_e32 v12, s8, v14
	v_mad_i64_i32 v[18:19], s[92:93], v12, s14, v[26:27]
	v_add_u32_e32 v14, 0x4800, v23
	v_lshl_add_u64 v[12:13], v[18:19], 0, s[72:73]
	v_readfirstlane_b32 s92, v14
	v_lshl_add_u64 v[12:13], v[12:13], 0, v[28:29]
	s_mov_b32 m0, s92
	v_add_u32_e32 v14, 0x4c00, v23
	global_load_lds_dwordx4 v[12:13], off
	v_add_u32_e32 v12, s8, v15
	v_mad_i64_i32 v[20:21], s[94:95], v12, s14, v[26:27]
	s_cmp_lg_u32 s5, 6
	v_lshl_add_u64 v[12:13], v[20:21], 0, s[72:73]
	v_readfirstlane_b32 s93, v14
	s_cselect_b32 s96, s5, 0
	v_lshl_add_u64 v[12:13], v[12:13], 0, v[28:29]
	s_mov_b32 m0, s93
	s_lshl_b32 s72, s96, 6
	global_load_lds_dwordx4 v[12:13], off
	v_lshl_add_u64 v[12:13], v[10:11], 0, v[28:29]
	v_lshl_add_u64 v[10:11], v[18:19], 0, v[28:29]
	v_or_b32_e32 v18, s72, v16
	v_add_u32_e32 v40, 0x8000, v23
	v_ashrrev_i32_e32 v19, 31, v18
	v_lshlrev_b64 v[18:19], 1, v[18:19]
	v_readfirstlane_b32 s5, v40
	v_add_u32_e32 v40, 0x8400, v23
	v_lshl_add_u64 v[14:15], v[8:9], 0, v[28:29]
	v_lshl_add_u64 v[8:9], v[20:21], 0, v[28:29]
	v_lshl_add_u64 v[20:21], v[0:1], 0, v[18:19]
	s_mov_b32 m0, s5
	v_readfirstlane_b32 s8, v40
	v_add_u32_e32 v40, 0x8800, v23
	s_waitcnt vmcnt(0) lgkmcnt(0)
	s_barrier
	global_load_lds_dwordx4 v[20:21], off
	v_lshl_add_u64 v[20:21], v[2:3], 0, v[18:19]
	s_mov_b32 m0, s8
	v_readfirstlane_b32 s57, v40
	global_load_lds_dwordx4 v[20:21], off
	v_lshl_add_u64 v[20:21], v[4:5], 0, v[18:19]
	s_mov_b32 m0, s57
	s_ashr_i32 s73, s72, 31
	global_load_lds_dwordx4 v[20:21], off
	v_add_u32_e32 v20, 0x8c00, v23
	v_lshl_add_u64 v[18:19], v[6:7], 0, v[18:19]
	v_readfirstlane_b32 s65, v20
	v_add_u32_e32 v20, 0xc000, v23
	s_mov_b32 m0, s65
	s_lshl_b64 s[94:95], s[72:73], 1
	v_readfirstlane_b32 s71, v20
	v_add_u32_e32 v20, 0xc400, v23
	global_load_lds_dwordx4 v[18:19], off
	v_lshl_add_u64 v[18:19], v[14:15], 0, s[94:95]
	s_mov_b32 m0, s71
	v_readfirstlane_b32 s72, v20
	v_add_u32_e32 v20, 0xc800, v23
	global_load_lds_dwordx4 v[18:19], off
	v_lshl_add_u64 v[18:19], v[12:13], 0, s[94:95]
	s_mov_b32 m0, s72
	v_readfirstlane_b32 s73, v20
	v_add_u32_e32 v20, 0xcc00, v23
	global_load_lds_dwordx4 v[18:19], off
	v_lshl_add_u64 v[18:19], v[10:11], 0, s[94:95]
	s_mov_b32 m0, s73
	v_readfirstlane_b32 s85, v20
	v_bfe_u32 v22, v17, 4, 2
	global_load_lds_dwordx4 v[18:19], off
	v_lshl_add_u64 v[18:19], v[8:9], 0, s[94:95]
	s_mov_b32 m0, s85
	v_and_b32_e32 v38, 15, v17
	v_bitop3_b32 v28, v22, v17, 7 bitop3:0x78
	global_load_lds_dwordx4 v[18:19], off
	s_setprio 1
	v_lshlrev_b32_e32 v18, 7, v17
	v_ashrrev_i32_e32 v39, 7, v17
	v_lshlrev_b32_e32 v23, 4, v28
	v_lshlrev_b32_e32 v28, 7, v38
	v_and_b32_e32 v80, 0x2780, v18
	v_or_b32_e32 v83, v23, v80
	v_lshl_or_b32 v28, v39, 13, v28
	ds_read_b128 v[18:21], v83 offset:16384
	v_or_b32_e32 v136, v23, v28
	ds_read_b128 v[40:43], v83 offset:18432
	ds_read_b128 v[44:47], v136
	ds_read_b128 v[48:51], v136 offset:2048
	ds_read_b128 v[56:59], v83 offset:20480
	ds_read_b128 v[64:67], v83 offset:22528
	ds_read_b128 v[88:91], v136 offset:4096
	ds_read_b128 v[92:95], v136 offset:6144
	v_and_b32_e32 v17, 7, v17
	v_bitop3_b32 v17, v22, v17, 4 bitop3:0x36
	v_lshlrev_b32_e32 v17, 4, v17
	v_or_b32_e32 v132, v17, v80
	s_waitcnt lgkmcnt(0)
	v_mfma_f32_16x16x32_bf16 v[52:55], v[18:21], v[44:47], 0
	ds_read_b128 v[108:111], v132 offset:16384
	v_or_b32_e32 v133, v17, v28
	s_add_i32 s96, s96, 1
	v_mfma_f32_16x16x32_bf16 v[60:63], v[40:43], v[44:47], 0
	s_cmp_lg_u32 s96, 6
	s_cselect_b32 s96, s96, 0
	s_lshl_b32 s94, s96, 6
	v_mfma_f32_16x16x32_bf16 v[68:71], v[56:59], v[44:47], 0
	v_or_b32_e32 v22, s94, v16
	v_ashrrev_i32_e32 v23, 31, v22
	v_lshlrev_b64 v[22:23], 1, v[22:23]
	v_mfma_f32_16x16x32_bf16 v[44:47], v[64:67], v[44:47], 0
	v_lshl_add_u64 v[80:81], v[0:1], 0, v[22:23]
	s_mov_b32 m0, s86
	s_ashr_i32 s95, s94, 31
	v_mfma_f32_16x16x32_bf16 v[72:75], v[18:21], v[48:51], 0
	s_lshl_b64 s[94:95], s[94:95], 1
	s_add_i32 s96, s96, 1
	s_cmp_lg_u32 s96, 6
	v_mfma_f32_16x16x32_bf16 v[76:79], v[40:43], v[48:51], 0
	s_cselect_b32 s96, s96, 0
	v_mfma_f32_16x16x32_bf16 v[84:87], v[56:59], v[48:51], 0
	v_mfma_f32_16x16x32_bf16 v[48:51], v[64:67], v[48:51], 0
	v_mfma_f32_16x16x32_bf16 v[96:99], v[18:21], v[88:91], 0
	v_mfma_f32_16x16x32_bf16 v[100:103], v[40:43], v[88:91], 0
	v_mfma_f32_16x16x32_bf16 v[104:107], v[56:59], v[88:91], 0
	v_mfma_f32_16x16x32_bf16 v[88:91], v[64:67], v[88:91], 0
	v_mfma_f32_16x16x32_bf16 v[18:21], v[18:21], v[92:95], 0
	v_mfma_f32_16x16x32_bf16 v[40:43], v[40:43], v[92:95], 0
	v_mfma_f32_16x16x32_bf16 v[56:59], v[56:59], v[92:95], 0
	v_mfma_f32_16x16x32_bf16 v[64:67], v[64:67], v[92:95], 0
	ds_read_b128 v[92:95], v132 offset:18432
	ds_read_b128 v[112:115], v133
	ds_read_b128 v[116:119], v133 offset:2048
	ds_read_b128 v[120:123], v132 offset:20480
	ds_read_b128 v[124:127], v132 offset:22528
	s_waitcnt lgkmcnt(3)
	v_mfma_f32_16x16x32_bf16 v[52:55], v[108:111], v[112:115], v[52:55]
	v_mfma_f32_16x16x32_bf16 v[60:63], v[92:95], v[112:115], v[60:63]
	s_waitcnt lgkmcnt(1)
	v_mfma_f32_16x16x32_bf16 v[68:71], v[120:123], v[112:115], v[68:71]
	s_waitcnt lgkmcnt(0)
	v_mfma_f32_16x16x32_bf16 v[44:47], v[124:127], v[112:115], v[44:47]
	v_mfma_f32_16x16x32_bf16 v[72:75], v[108:111], v[116:119], v[72:75]
	v_mfma_f32_16x16x32_bf16 v[76:79], v[92:95], v[116:119], v[76:79]
	v_mfma_f32_16x16x32_bf16 v[84:87], v[120:123], v[116:119], v[84:87]
	v_mfma_f32_16x16x32_bf16 v[48:51], v[124:127], v[116:119], v[48:51]
	ds_read_b128 v[112:115], v133 offset:4096
	ds_read_b128 v[116:119], v133 offset:6144
	s_setprio 0
	s_waitcnt vmcnt(0) lgkmcnt(0)
	s_barrier
	global_load_lds_dwordx4 v[80:81], off
	v_lshl_add_u64 v[80:81], v[2:3], 0, v[22:23]
	s_mov_b32 m0, s87
	v_mfma_f32_16x16x32_bf16 v[96:99], v[108:111], v[112:115], v[96:99]
	global_load_lds_dwordx4 v[80:81], off
	v_lshl_add_u64 v[80:81], v[4:5], 0, v[22:23]
	s_mov_b32 m0, s88
	v_lshl_add_u64 v[22:23], v[6:7], 0, v[22:23]
	global_load_lds_dwordx4 v[80:81], off
	s_mov_b32 m0, s89
	v_mfma_f32_16x16x32_bf16 v[100:103], v[92:95], v[112:115], v[100:103]
	global_load_lds_dwordx4 v[22:23], off
	v_lshl_add_u64 v[22:23], v[14:15], 0, s[94:95]
	s_mov_b32 m0, s90
	v_mfma_f32_16x16x32_bf16 v[104:107], v[120:123], v[112:115], v[104:107]
	global_load_lds_dwordx4 v[22:23], off
	v_lshl_add_u64 v[22:23], v[12:13], 0, s[94:95]
	s_mov_b32 m0, s91
	v_mfma_f32_16x16x32_bf16 v[88:91], v[124:127], v[112:115], v[88:91]
	global_load_lds_dwordx4 v[22:23], off
	v_lshl_add_u64 v[22:23], v[10:11], 0, s[94:95]
	s_mov_b32 m0, s92
	v_mfma_f32_16x16x32_bf16 v[18:21], v[108:111], v[116:119], v[18:21]
	global_load_lds_dwordx4 v[22:23], off
	v_lshl_add_u64 v[22:23], v[8:9], 0, s[94:95]
	s_mov_b32 m0, s93
	v_mfma_f32_16x16x32_bf16 v[40:43], v[92:95], v[116:119], v[40:43]
	global_load_lds_dwordx4 v[22:23], off
	s_setprio 1
	ds_read_b128 v[92:95], v83 offset:49152
	v_mfma_f32_16x16x32_bf16 v[56:59], v[120:123], v[116:119], v[56:59]
	s_lshl_b32 s94, s96, 6
	v_or_b32_e32 v22, s94, v16
	v_ashrrev_i32_e32 v23, 31, v22
	v_mfma_f32_16x16x32_bf16 v[64:67], v[124:127], v[116:119], v[64:67]
	ds_read_b128 v[108:111], v83 offset:51200
	ds_read_b128 v[112:115], v136 offset:32768
	ds_read_b128 v[116:119], v136 offset:34816
	ds_read_b128 v[120:123], v83 offset:53248
	ds_read_b128 v[124:127], v83 offset:55296
	s_waitcnt lgkmcnt(0)
	v_mfma_f32_16x16x32_bf16 v[52:55], v[92:95], v[112:115], v[52:55]
	v_lshlrev_b64 v[22:23], 1, v[22:23]
	v_lshl_add_u64 v[80:81], v[0:1], 0, v[22:23]
	s_mov_b32 m0, s5
	v_mfma_f32_16x16x32_bf16 v[60:63], v[108:111], v[112:115], v[60:63]
	s_ashr_i32 s95, s94, 31
	s_lshl_b64 s[94:95], s[94:95], 1
	s_add_i32 s96, s96, 1
	v_mfma_f32_16x16x32_bf16 v[68:71], v[120:123], v[112:115], v[68:71]
	s_cmp_lg_u32 s96, 6
	s_cselect_b32 s96, s96, 0
	v_mfma_f32_16x16x32_bf16 v[44:47], v[124:127], v[112:115], v[44:47]
	v_mfma_f32_16x16x32_bf16 v[72:75], v[92:95], v[116:119], v[72:75]
	v_mfma_f32_16x16x32_bf16 v[76:79], v[108:111], v[116:119], v[76:79]
	v_mfma_f32_16x16x32_bf16 v[84:87], v[120:123], v[116:119], v[84:87]
	v_mfma_f32_16x16x32_bf16 v[48:51], v[124:127], v[116:119], v[48:51]
	ds_read_b128 v[112:115], v136 offset:36864
	ds_read_b128 v[116:119], v136 offset:38912
	s_waitcnt lgkmcnt(1)
	v_mfma_f32_16x16x32_bf16 v[96:99], v[92:95], v[112:115], v[96:99]
	v_mfma_f32_16x16x32_bf16 v[100:103], v[108:111], v[112:115], v[100:103]
	v_mfma_f32_16x16x32_bf16 v[104:107], v[120:123], v[112:115], v[104:107]
	v_mfma_f32_16x16x32_bf16 v[88:91], v[124:127], v[112:115], v[88:91]
	s_waitcnt lgkmcnt(0)
	v_mfma_f32_16x16x32_bf16 v[18:21], v[92:95], v[116:119], v[18:21]
	ds_read_b128 v[92:95], v132 offset:49152
	v_mfma_f32_16x16x32_bf16 v[40:43], v[108:111], v[116:119], v[40:43]
	v_mfma_f32_16x16x32_bf16 v[56:59], v[120:123], v[116:119], v[56:59]
	v_mfma_f32_16x16x32_bf16 v[64:67], v[124:127], v[116:119], v[64:67]
	ds_read_b128 v[108:111], v132 offset:51200
	ds_read_b128 v[112:115], v133 offset:32768
	ds_read_b128 v[116:119], v133 offset:34816
	ds_read_b128 v[120:123], v132 offset:53248
	ds_read_b128 v[124:127], v132 offset:55296
	s_waitcnt lgkmcnt(3)
	v_mfma_f32_16x16x32_bf16 v[52:55], v[92:95], v[112:115], v[52:55]
	v_mfma_f32_16x16x32_bf16 v[60:63], v[108:111], v[112:115], v[60:63]
	s_waitcnt lgkmcnt(1)
	v_mfma_f32_16x16x32_bf16 v[68:71], v[120:123], v[112:115], v[68:71]
	s_waitcnt lgkmcnt(0)
	v_mfma_f32_16x16x32_bf16 v[44:47], v[124:127], v[112:115], v[44:47]
	v_mfma_f32_16x16x32_bf16 v[72:75], v[92:95], v[116:119], v[72:75]
	v_mfma_f32_16x16x32_bf16 v[76:79], v[108:111], v[116:119], v[76:79]
	v_mfma_f32_16x16x32_bf16 v[84:87], v[120:123], v[116:119], v[84:87]
	v_mfma_f32_16x16x32_bf16 v[48:51], v[124:127], v[116:119], v[48:51]
	ds_read_b128 v[112:115], v133 offset:36864
	ds_read_b128 v[116:119], v133 offset:38912
	s_setprio 0
	s_waitcnt vmcnt(0) lgkmcnt(0)
	s_barrier
	global_load_lds_dwordx4 v[80:81], off
	v_lshl_add_u64 v[80:81], v[2:3], 0, v[22:23]
	s_mov_b32 m0, s8
	v_mfma_f32_16x16x32_bf16 v[96:99], v[92:95], v[112:115], v[96:99]
	global_load_lds_dwordx4 v[80:81], off
	v_lshl_add_u64 v[80:81], v[4:5], 0, v[22:23]
	s_mov_b32 m0, s57
	v_lshl_add_u64 v[22:23], v[6:7], 0, v[22:23]
	global_load_lds_dwordx4 v[80:81], off
	s_mov_b32 m0, s65
	v_mfma_f32_16x16x32_bf16 v[100:103], v[108:111], v[112:115], v[100:103]
	global_load_lds_dwordx4 v[22:23], off
	v_lshl_add_u64 v[22:23], v[14:15], 0, s[94:95]
	s_mov_b32 m0, s71
	v_mfma_f32_16x16x32_bf16 v[104:107], v[120:123], v[112:115], v[104:107]
	global_load_lds_dwordx4 v[22:23], off
	v_lshl_add_u64 v[22:23], v[12:13], 0, s[94:95]
	s_mov_b32 m0, s72
	v_mfma_f32_16x16x32_bf16 v[88:91], v[124:127], v[112:115], v[88:91]
	global_load_lds_dwordx4 v[22:23], off
	v_lshl_add_u64 v[22:23], v[10:11], 0, s[94:95]
	s_mov_b32 m0, s73
	v_mfma_f32_16x16x32_bf16 v[18:21], v[92:95], v[116:119], v[18:21]
	global_load_lds_dwordx4 v[22:23], off
	v_lshl_add_u64 v[22:23], v[8:9], 0, s[94:95]
	s_mov_b32 m0, s85
	v_mfma_f32_16x16x32_bf16 v[40:43], v[108:111], v[116:119], v[40:43]
	global_load_lds_dwordx4 v[22:23], off
	s_setprio 1
	ds_read_b128 v[92:95], v83 offset:16384
	v_mfma_f32_16x16x32_bf16 v[56:59], v[120:123], v[116:119], v[56:59]
	s_lshl_b32 s94, s96, 6
	v_or_b32_e32 v22, s94, v16
	v_ashrrev_i32_e32 v23, 31, v22
	v_mfma_f32_16x16x32_bf16 v[64:67], v[124:127], v[116:119], v[64:67]
	ds_read_b128 v[108:111], v83 offset:18432
	ds_read_b128 v[112:115], v136
	ds_read_b128 v[116:119], v136 offset:2048
	ds_read_b128 v[120:123], v83 offset:20480
	ds_read_b128 v[124:127], v83 offset:22528
	s_waitcnt lgkmcnt(0)
	v_mfma_f32_16x16x32_bf16 v[52:55], v[92:95], v[112:115], v[52:55]
	v_lshlrev_b64 v[22:23], 1, v[22:23]
	v_lshl_add_u64 v[80:81], v[0:1], 0, v[22:23]
	s_mov_b32 m0, s86
	v_mfma_f32_16x16x32_bf16 v[60:63], v[108:111], v[112:115], v[60:63]
	s_ashr_i32 s95, s94, 31
	s_add_i32 s96, s96, 1
	v_mfma_f32_16x16x32_bf16 v[68:71], v[120:123], v[112:115], v[68:71]
	v_mfma_f32_16x16x32_bf16 v[44:47], v[124:127], v[112:115], v[44:47]
	v_mfma_f32_16x16x32_bf16 v[72:75], v[92:95], v[116:119], v[72:75]
	v_mfma_f32_16x16x32_bf16 v[76:79], v[108:111], v[116:119], v[76:79]
	v_mfma_f32_16x16x32_bf16 v[84:87], v[120:123], v[116:119], v[84:87]
	v_mfma_f32_16x16x32_bf16 v[48:51], v[124:127], v[116:119], v[48:51]
	ds_read_b128 v[112:115], v136 offset:4096
	ds_read_b128 v[116:119], v136 offset:6144
	s_waitcnt lgkmcnt(1)
	v_mfma_f32_16x16x32_bf16 v[96:99], v[92:95], v[112:115], v[96:99]
	v_mfma_f32_16x16x32_bf16 v[100:103], v[108:111], v[112:115], v[100:103]
	v_mfma_f32_16x16x32_bf16 v[104:107], v[120:123], v[112:115], v[104:107]
	v_mfma_f32_16x16x32_bf16 v[88:91], v[124:127], v[112:115], v[88:91]
	s_waitcnt lgkmcnt(0)
	v_mfma_f32_16x16x32_bf16 v[18:21], v[92:95], v[116:119], v[18:21]
	ds_read_b128 v[92:95], v132 offset:16384
	v_mfma_f32_16x16x32_bf16 v[40:43], v[108:111], v[116:119], v[40:43]
	v_mfma_f32_16x16x32_bf16 v[56:59], v[120:123], v[116:119], v[56:59]
	v_mfma_f32_16x16x32_bf16 v[64:67], v[124:127], v[116:119], v[64:67]
	ds_read_b128 v[108:111], v132 offset:18432
	ds_read_b128 v[112:115], v133
	ds_read_b128 v[116:119], v133 offset:2048
	ds_read_b128 v[120:123], v132 offset:20480
	ds_read_b128 v[124:127], v132 offset:22528
	s_waitcnt lgkmcnt(3)
	v_mfma_f32_16x16x32_bf16 v[52:55], v[92:95], v[112:115], v[52:55]
	v_mfma_f32_16x16x32_bf16 v[60:63], v[108:111], v[112:115], v[60:63]
	s_waitcnt lgkmcnt(1)
	v_mfma_f32_16x16x32_bf16 v[68:71], v[120:123], v[112:115], v[68:71]
	s_waitcnt lgkmcnt(0)
	v_mfma_f32_16x16x32_bf16 v[44:47], v[124:127], v[112:115], v[44:47]
	v_mfma_f32_16x16x32_bf16 v[72:75], v[92:95], v[116:119], v[72:75]
	v_mfma_f32_16x16x32_bf16 v[76:79], v[108:111], v[116:119], v[76:79]
	v_mfma_f32_16x16x32_bf16 v[84:87], v[120:123], v[116:119], v[84:87]
	v_mfma_f32_16x16x32_bf16 v[48:51], v[124:127], v[116:119], v[48:51]
	ds_read_b128 v[112:115], v133 offset:4096
	ds_read_b128 v[116:119], v133 offset:6144
	s_setprio 0
	s_waitcnt vmcnt(0) lgkmcnt(0)
	s_barrier
	global_load_lds_dwordx4 v[80:81], off
	v_lshl_add_u64 v[80:81], v[2:3], 0, v[22:23]
	s_mov_b32 m0, s87
	s_lshl_b64 s[86:87], s[94:95], 1
	global_load_lds_dwordx4 v[80:81], off
	v_lshl_add_u64 v[80:81], v[4:5], 0, v[22:23]
	s_mov_b32 m0, s88
	v_lshl_add_u64 v[22:23], v[6:7], 0, v[22:23]
	global_load_lds_dwordx4 v[80:81], off
	s_mov_b32 m0, s89
	v_mfma_f32_16x16x32_bf16 v[96:99], v[92:95], v[112:115], v[96:99]
	global_load_lds_dwordx4 v[22:23], off
	v_lshl_add_u64 v[22:23], v[14:15], 0, s[86:87]
	s_mov_b32 m0, s90
	v_mfma_f32_16x16x32_bf16 v[100:103], v[108:111], v[112:115], v[100:103]
	global_load_lds_dwordx4 v[22:23], off
	v_lshl_add_u64 v[22:23], v[12:13], 0, s[86:87]
	s_mov_b32 m0, s91
	v_mfma_f32_16x16x32_bf16 v[104:107], v[120:123], v[112:115], v[104:107]
	global_load_lds_dwordx4 v[22:23], off
	v_lshl_add_u64 v[22:23], v[10:11], 0, s[86:87]
	s_mov_b32 m0, s92
	v_mfma_f32_16x16x32_bf16 v[88:91], v[124:127], v[112:115], v[88:91]
	global_load_lds_dwordx4 v[22:23], off
	v_lshl_add_u64 v[22:23], v[8:9], 0, s[86:87]
	s_mov_b32 m0, s93
	v_mfma_f32_16x16x32_bf16 v[18:21], v[92:95], v[116:119], v[18:21]
	global_load_lds_dwordx4 v[22:23], off
	s_setprio 1
	ds_read_b128 v[92:95], v83 offset:49152
	v_mfma_f32_16x16x32_bf16 v[40:43], v[108:111], v[116:119], v[40:43]
	s_lshl_b32 s86, s96, 6
	s_cmp_lg_u32 s96, 6
	s_cselect_b32 s86, s86, 0
	v_mfma_f32_16x16x32_bf16 v[56:59], v[120:123], v[116:119], v[56:59]
	v_or_b32_e32 v16, s86, v16
	v_lshlrev_b32_e32 v28, 1, v16
	v_lshl_add_u64 v[0:1], v[0:1], 0, v[28:29]
	v_mfma_f32_16x16x32_bf16 v[64:67], v[124:127], v[116:119], v[64:67]
	ds_read_b128 v[108:111], v83 offset:51200
	ds_read_b128 v[112:115], v136 offset:32768
	ds_read_b128 v[116:119], v136 offset:34816
	ds_read_b128 v[120:123], v83 offset:53248
	ds_read_b128 v[124:127], v83 offset:55296
	s_waitcnt lgkmcnt(0)
	v_mfma_f32_16x16x32_bf16 v[52:55], v[92:95], v[112:115], v[52:55]
	s_mov_b32 m0, s5
	v_mfma_f32_16x16x32_bf16 v[60:63], v[108:111], v[112:115], v[60:63]
	v_mfma_f32_16x16x32_bf16 v[68:71], v[120:123], v[112:115], v[68:71]
	v_mfma_f32_16x16x32_bf16 v[44:47], v[124:127], v[112:115], v[44:47]
	v_mfma_f32_16x16x32_bf16 v[72:75], v[92:95], v[116:119], v[72:75]
	v_mfma_f32_16x16x32_bf16 v[76:79], v[108:111], v[116:119], v[76:79]
	v_mfma_f32_16x16x32_bf16 v[84:87], v[120:123], v[116:119], v[84:87]
	v_mfma_f32_16x16x32_bf16 v[48:51], v[124:127], v[116:119], v[48:51]
	ds_read_b128 v[112:115], v136 offset:36864
	ds_read_b128 v[116:119], v136 offset:38912
	s_waitcnt lgkmcnt(1)
	v_mfma_f32_16x16x32_bf16 v[96:99], v[92:95], v[112:115], v[96:99]
	v_mfma_f32_16x16x32_bf16 v[100:103], v[108:111], v[112:115], v[100:103]
	v_mfma_f32_16x16x32_bf16 v[104:107], v[120:123], v[112:115], v[104:107]
	v_mfma_f32_16x16x32_bf16 v[88:91], v[124:127], v[112:115], v[88:91]
	s_waitcnt lgkmcnt(0)
	v_mfma_f32_16x16x32_bf16 v[18:21], v[92:95], v[116:119], v[18:21]
	ds_read_b128 v[92:95], v132 offset:49152
	v_mfma_f32_16x16x32_bf16 v[40:43], v[108:111], v[116:119], v[40:43]
	v_mfma_f32_16x16x32_bf16 v[56:59], v[120:123], v[116:119], v[56:59]
	v_mfma_f32_16x16x32_bf16 v[64:67], v[124:127], v[116:119], v[64:67]
	ds_read_b128 v[108:111], v132 offset:51200
	ds_read_b128 v[112:115], v133 offset:32768
	ds_read_b128 v[116:119], v133 offset:34816
	ds_read_b128 v[120:123], v132 offset:53248
	ds_read_b128 v[124:127], v132 offset:55296
	s_waitcnt lgkmcnt(3)
	v_mfma_f32_16x16x32_bf16 v[52:55], v[92:95], v[112:115], v[52:55]
	v_mfma_f32_16x16x32_bf16 v[60:63], v[108:111], v[112:115], v[60:63]
	s_waitcnt lgkmcnt(1)
	v_mfma_f32_16x16x32_bf16 v[68:71], v[120:123], v[112:115], v[68:71]
	s_waitcnt lgkmcnt(0)
	v_mfma_f32_16x16x32_bf16 v[44:47], v[124:127], v[112:115], v[44:47]
	v_mfma_f32_16x16x32_bf16 v[72:75], v[92:95], v[116:119], v[72:75]
	v_mfma_f32_16x16x32_bf16 v[76:79], v[108:111], v[116:119], v[76:79]
	v_mfma_f32_16x16x32_bf16 v[84:87], v[120:123], v[116:119], v[84:87]
	v_mfma_f32_16x16x32_bf16 v[48:51], v[124:127], v[116:119], v[48:51]
	ds_read_b128 v[112:115], v133 offset:36864
	ds_read_b128 v[116:119], v133 offset:38912
	s_setprio 0
	s_waitcnt vmcnt(0) lgkmcnt(0)
	s_barrier
	global_load_lds_dwordx4 v[0:1], off
	v_lshl_add_u64 v[0:1], v[2:3], 0, v[28:29]
	s_mov_b32 m0, s8
	s_lshl_b32 s8, s86, 1
	global_load_lds_dwordx4 v[0:1], off
	v_lshl_add_u64 v[0:1], v[4:5], 0, v[28:29]
	s_mov_b32 m0, s57
	v_mfma_f32_16x16x32_bf16 v[96:99], v[92:95], v[112:115], v[96:99]
	global_load_lds_dwordx4 v[0:1], off
	v_lshl_add_u64 v[0:1], v[6:7], 0, v[28:29]
	s_mov_b32 m0, s65
	v_mfma_f32_16x16x32_bf16 v[100:103], v[108:111], v[112:115], v[100:103]
	global_load_lds_dwordx4 v[0:1], off
	v_lshl_add_u64 v[0:1], v[14:15], 0, s[8:9]
	s_mov_b32 m0, s71
	v_mfma_f32_16x16x32_bf16 v[18:21], v[92:95], v[116:119], v[18:21]
	global_load_lds_dwordx4 v[0:1], off
	v_lshl_add_u64 v[0:1], v[12:13], 0, s[8:9]
	s_mov_b32 m0, s72
	v_mfma_f32_16x16x32_bf16 v[40:43], v[108:111], v[116:119], v[40:43]
	global_load_lds_dwordx4 v[0:1], off
	v_lshl_add_u64 v[0:1], v[10:11], 0, s[8:9]
	s_mov_b32 m0, s73
	v_mfma_f32_16x16x32_bf16 v[4:7], v[124:127], v[116:119], v[64:67]
	global_load_lds_dwordx4 v[0:1], off
	v_lshl_add_u64 v[0:1], v[8:9], 0, s[8:9]
	s_mov_b32 m0, s85
	v_mfma_f32_16x16x32_bf16 v[104:107], v[120:123], v[112:115], v[104:107]
	global_load_lds_dwordx4 v[0:1], off
	s_setprio 1
	ds_read_b128 v[0:3], v83 offset:16384
	ds_read_b128 v[8:11], v83 offset:18432
	ds_read_b128 v[12:15], v136
	ds_read_b128 v[64:67], v136 offset:2048
	ds_read_b128 v[92:95], v83 offset:20480
	ds_read_b128 v[108:111], v83 offset:22528
	s_waitcnt lgkmcnt(0)
	v_mfma_f32_16x16x32_bf16 v[52:55], v[0:3], v[12:15], v[52:55]
	v_lshl_add_u32 v28, v39, 6, s4
	v_or_b32_e32 v38, v28, v38
	v_ashrrev_i32_e32 v39, 31, v38
	v_mfma_f32_16x16x32_bf16 v[60:63], v[8:11], v[12:15], v[60:63]
	v_lshl_add_u64 v[38:39], v[38:39], 2, s[6:7]
	v_mfma_f32_16x16x32_bf16 v[68:71], v[92:95], v[12:15], v[68:71]
	v_mfma_f32_16x16x32_bf16 v[12:15], v[108:111], v[12:15], v[44:47]
	v_mfma_f32_16x16x32_bf16 v[44:47], v[0:3], v[64:67], v[72:75]
	v_mfma_f32_16x16x32_bf16 v[72:75], v[8:11], v[64:67], v[76:79]
	v_mfma_f32_16x16x32_bf16 v[76:79], v[92:95], v[64:67], v[84:87]
	v_mfma_f32_16x16x32_bf16 v[48:51], v[108:111], v[64:67], v[48:51]
	ds_read_b128 v[64:67], v136 offset:4096
	s_nop 0
	ds_read_b128 v[84:87], v136 offset:6144
	v_mfma_f32_16x16x32_bf16 v[88:91], v[124:127], v[112:115], v[88:91]
	v_mfma_f32_16x16x32_bf16 v[56:59], v[120:123], v[116:119], v[56:59]
	s_waitcnt lgkmcnt(1)
	v_mfma_f32_16x16x32_bf16 v[96:99], v[0:3], v[64:67], v[96:99]
	v_mfma_f32_16x16x32_bf16 v[100:103], v[8:11], v[64:67], v[100:103]
	v_mfma_f32_16x16x32_bf16 v[104:107], v[92:95], v[64:67], v[104:107]
	v_mfma_f32_16x16x32_bf16 v[64:67], v[108:111], v[64:67], v[88:91]
	s_waitcnt lgkmcnt(0)
	v_mfma_f32_16x16x32_bf16 v[88:91], v[0:3], v[84:87], v[18:21]
	v_mfma_f32_16x16x32_bf16 v[40:43], v[8:11], v[84:87], v[40:43]
	v_mfma_f32_16x16x32_bf16 v[56:59], v[92:95], v[84:87], v[56:59]
	ds_read_b128 v[92:95], v132 offset:16384
	v_mfma_f32_16x16x32_bf16 v[84:87], v[108:111], v[84:87], v[4:7]
	ds_read_b128 v[108:111], v132 offset:18432
	ds_read_b128 v[0:3], v133
	s_nop 0
	ds_read_b128 v[4:7], v133 offset:2048
	ds_read_b128 v[112:115], v132 offset:20480
	ds_read_b128 v[116:119], v132 offset:22528
	ds_read_b128 v[124:127], v133 offset:4096
	ds_read_b128 v[128:131], v133 offset:6144
	s_waitcnt lgkmcnt(5)
	v_mfma_f32_16x16x32_bf16 v[52:55], v[92:95], v[0:3], v[52:55]
	s_setprio 0
	s_waitcnt vmcnt(0) lgkmcnt(0)
	s_barrier
	v_mfma_f32_16x16x32_bf16 v[60:63], v[108:111], v[0:3], v[60:63]
	v_mfma_f32_16x16x32_bf16 v[68:71], v[112:115], v[0:3], v[68:71]
	v_mfma_f32_16x16x32_bf16 v[120:123], v[116:119], v[0:3], v[12:15]
	ds_read_b128 v[0:3], v132 offset:55296
	ds_read_b128 v[8:11], v132 offset:53248
	v_mfma_f32_16x16x32_bf16 v[44:47], v[92:95], v[4:7], v[44:47]
	v_mfma_f32_16x16x32_bf16 v[72:75], v[108:111], v[4:7], v[72:75]
	v_mfma_f32_16x16x32_bf16 v[76:79], v[112:115], v[4:7], v[76:79]
	v_mfma_f32_16x16x32_bf16 v[48:51], v[116:119], v[4:7], v[48:51]
	ds_read_b128 v[4:7], v133 offset:38912
	ds_read_b128 v[20:23], v133 offset:36864
	ds_read_b128 v[12:15], v132 offset:51200
	ds_read_b128 v[16:19], v132 offset:49152
	v_mfma_f32_16x16x32_bf16 v[96:99], v[92:95], v[124:127], v[96:99]
	v_mfma_f32_16x16x32_bf16 v[100:103], v[108:111], v[124:127], v[100:103]
	v_mfma_f32_16x16x32_bf16 v[104:107], v[112:115], v[124:127], v[104:107]
	v_mfma_f32_16x16x32_bf16 v[64:67], v[116:119], v[124:127], v[64:67]
	ds_read_b128 v[124:127], v133 offset:34816
	ds_read_b128 v[132:135], v133 offset:32768
	ds_read_b128 v[140:143], v83 offset:55296
	ds_read_b128 v[144:147], v83 offset:53248
	v_mfma_f32_16x16x32_bf16 v[88:91], v[92:95], v[128:131], v[88:91]
	ds_read_b128 v[92:95], v136 offset:38912
	ds_read_b128 v[148:151], v136 offset:36864
	ds_read_b128 v[152:155], v83 offset:51200
	ds_read_b128 v[156:159], v83 offset:49152
	v_mfma_f32_16x16x32_bf16 v[40:43], v[108:111], v[128:131], v[40:43]
	ds_read_b128 v[108:111], v136 offset:34816
	ds_read_b128 v[160:163], v136 offset:32768
	s_waitcnt lgkmcnt(0)
	s_barrier
	global_load_dword v28, v[38:39], off
	global_load_dword v80, v[38:39], off offset:64
	global_load_dword v81, v[38:39], off offset:128
	v_mfma_f32_16x16x32_bf16 v[56:59], v[112:115], v[128:131], v[56:59]
	global_load_dword v38, v[38:39], off offset:192
	s_waitcnt vmcnt(3)
	v_fmamk_f32 v28, v28, 0x3b2aaaab, v31
	v_mul_f32_e32 v39, 0x4b800000, v28
	v_cmp_gt_f32_e32 vcc, s13, v28
	v_mfma_f32_16x16x32_bf16 v[84:87], v[116:119], v[128:131], v[84:87]
	s_waitcnt vmcnt(0)
	v_fmamk_f32 v38, v38, 0x3b2aaaab, v31
	v_cndmask_b32_e32 v28, v28, v39, vcc
	v_fmamk_f32 v39, v80, 0x3b2aaaab, v31
	v_mul_f32_e32 v80, 0x4b800000, v39
	v_cmp_gt_f32_e64 s[4:5], s13, v39
	v_rsq_f32_e32 v28, v28
	v_mfma_f32_16x16x32_bf16 v[44:47], v[156:159], v[108:111], v[44:47]
	v_cndmask_b32_e64 v39, v39, v80, s[4:5]
	v_rsq_f32_e32 v39, v39
	v_mul_f32_e32 v80, 0x45800000, v28
	v_cndmask_b32_e32 v28, v28, v80, vcc
	v_mfma_f32_16x16x32_bf16 v[72:75], v[152:155], v[108:111], v[72:75]
	v_mul_f32_e32 v80, 0x45800000, v39
	v_cndmask_b32_e64 v80, v39, v80, s[4:5]
	v_fmamk_f32 v39, v81, 0x3b2aaaab, v31
	v_mul_f32_e32 v81, 0x4b800000, v39
	v_cmp_gt_f32_e32 vcc, s13, v39
	v_cmp_gt_f32_e64 s[4:5], s13, v38
	v_mfma_f32_16x16x32_bf16 v[76:79], v[144:147], v[108:111], v[76:79]
	v_cndmask_b32_e32 v39, v39, v81, vcc
	v_mul_f32_e32 v81, 0x4b800000, v38
	v_rsq_f32_e32 v39, v39
	v_cndmask_b32_e64 v38, v38, v81, s[4:5]
	v_rsq_f32_e32 v38, v38
	v_mfma_f32_16x16x32_bf16 v[48:51], v[140:143], v[108:111], v[48:51]
	v_mul_f32_e32 v81, 0x45800000, v39
	v_cndmask_b32_e32 v108, v39, v81, vcc
	v_mul_f32_e32 v39, 0x45800000, v38
	v_mov_b32_e32 v81, v138
	v_cndmask_b32_e64 v110, v38, v39, s[4:5]
	v_mfma_f32_16x16x32_bf16 v[38:41], v[152:155], v[92:95], v[40:43]
	v_cmp_lt_i32_e32 vcc, v34, v35
	v_lshrrev_b32_e32 v83, 1, v81
	v_mfma_f32_16x16x32_bf16 v[88:91], v[156:159], v[92:95], v[88:91]
	v_and_b32_e32 v43, 15, v81
	v_and_b32_e32 v42, 64, v81
	v_and_or_b32 v43, v83, s31, v43
	v_and_b32_e32 v83, 48, v81
	v_lshl_or_b32 v42, v42, 2, v83
	v_mfma_f32_16x16x32_bf16 v[56:59], v[144:147], v[92:95], v[56:59]
	v_mfma_f32_16x16x32_bf16 v[84:87], v[140:143], v[92:95], v[84:87]
	v_mad_u64_u32 v[92:93], s[4:5], v43, s34, v[42:43]
	s_mul_i32 s4, s51, 0x60
	v_mfma_f32_16x16x32_bf16 v[42:45], v[16:19], v[124:127], v[44:47]
	s_ashr_i32 s5, s4, 31
	s_lshl_b64 s[4:5], s[4:5], 1
	s_add_u32 s4, s78, s4
	v_mfma_f32_16x16x32_bf16 v[52:55], v[156:159], v[160:163], v[52:55]
	s_addc_u32 s5, s79, s5
	s_nop 2
	v_pk_mul_f32 v[44:45], v[44:45], v[80:81] op_sel_hi:[1,0]
	v_pk_mul_f32 v[42:43], v[42:43], v[80:81] op_sel_hi:[1,0]
	ds_write_b128 v92, v[42:45] offset:8448
	v_mfma_f32_16x16x32_bf16 v[42:45], v[12:15], v[124:127], v[72:75]
	s_lshl_b32 s8, s50, 7
	s_and_b32 s8, s8, 0xfffffc00
	s_or_b32 s8, s8, s30
	v_mfma_f32_16x16x32_bf16 v[52:55], v[16:19], v[132:135], v[52:55]
	v_mfma_f32_16x16x32_bf16 v[60:63], v[152:155], v[160:163], v[60:63]
	s_nop 2
	v_mul_f32_e64 v44, v44, v80
	v_mul_f32_e64 v45, v45, v80
	v_pk_mul_f32 v[42:43], v[42:43], v[80:81] op_sel_hi:[1,0]
	ds_write_b128 v92, v[42:45] offset:8512
	v_mfma_f32_16x16x32_bf16 v[42:45], v[8:11], v[124:127], v[76:79]
	v_mul_f32_e64 v54, v54, v28
	v_mul_f32_e64 v55, v55, v28
	v_pk_mul_f32 v[52:53], v[52:53], v[28:29] op_sel_hi:[1,0]
	ds_write_b128 v92, v[52:55]
	v_mfma_f32_16x16x32_bf16 v[96:99], v[156:159], v[148:151], v[96:99]
	v_mfma_f32_16x16x32_bf16 v[52:55], v[12:15], v[132:135], v[60:63]
	s_nop 1
	v_mul_f32_e64 v44, v44, v80
	v_mul_f32_e64 v45, v45, v80
	v_pk_mul_f32 v[42:43], v[42:43], v[80:81] op_sel_hi:[1,0]
	ds_write_b128 v92, v[42:45] offset:8576
	v_mfma_f32_16x16x32_bf16 v[42:45], v[0:3], v[124:127], v[48:51]
	v_mfma_f32_16x16x32_bf16 v[68:71], v[144:147], v[160:163], v[68:71]
	v_mul_f32_e64 v54, v54, v28
	v_mul_f32_e64 v55, v55, v28
	s_nop 4
	v_pk_mul_f32 v[44:45], v[44:45], v[80:81] op_sel_hi:[1,0]
	v_pk_mul_f32 v[42:43], v[42:43], v[80:81] op_sel_hi:[1,0]
	ds_write_b128 v92, v[42:45] offset:8640
	v_mfma_f32_16x16x32_bf16 v[42:45], v[16:19], v[20:23], v[96:99]
	v_mul_f32_e64 v52, v52, v28
	v_mul_f32_e64 v53, v53, v28
	ds_write_b128 v92, v[52:55] offset:64
	v_mfma_f32_16x16x32_bf16 v[100:103], v[152:155], v[148:151], v[100:103]
	v_mfma_f32_16x16x32_bf16 v[52:55], v[8:11], v[132:135], v[68:71]
	s_nop 2
	v_mul_f32_e64 v44, v44, v108
	v_mul_f32_e64 v45, v45, v108
	v_pk_mul_f32 v[42:43], v[42:43], v[108:109] op_sel_hi:[1,0]
	ds_write_b128 v92, v[42:45] offset:16896
	v_mfma_f32_16x16x32_bf16 v[42:45], v[12:15], v[20:23], v[100:103]
	v_mfma_f32_16x16x32_bf16 v[112:115], v[140:143], v[160:163], v[120:123]
	v_mul_f32_e64 v54, v54, v28
	v_mul_f32_e64 v55, v55, v28
	v_pk_mul_f32 v[52:53], v[52:53], v[28:29] op_sel_hi:[1,0]
	s_nop 3
	v_pk_mul_f32 v[44:45], v[44:45], v[108:109] op_sel_hi:[1,0]
	v_mfma_f32_16x16x32_bf16 v[104:107], v[144:147], v[148:151], v[104:107]
	v_mul_f32_e64 v42, v42, v108
	v_mul_f32_e64 v43, v43, v108
	ds_write_b128 v92, v[52:55] offset:128
	ds_write_b128 v92, v[42:45] offset:16960
	v_mfma_f32_16x16x32_bf16 v[64:67], v[140:143], v[148:151], v[64:67]
	v_mfma_f32_16x16x32_bf16 v[52:55], v[0:3], v[132:135], v[112:115]
	v_mfma_f32_16x16x32_bf16 v[42:45], v[8:11], v[20:23], v[104:107]
	v_mfma_f32_16x16x32_bf16 v[20:23], v[0:3], v[20:23], v[64:67]
	s_nop 5
	v_mul_f32_e64 v54, v54, v28
	v_mul_f32_e64 v55, v55, v28
	v_pk_mul_f32 v[52:53], v[52:53], v[28:29] op_sel_hi:[1,0]
	v_pk_mul_f32 v[44:45], v[44:45], v[108:109] op_sel_hi:[1,0]
	v_mfma_f32_16x16x32_bf16 v[0:3], v[0:3], v[4:7], v[84:87]
	v_mul_f32_e64 v42, v42, v108
	v_mul_f32_e64 v43, v43, v108
	v_pk_mul_f32 v[22:23], v[22:23], v[108:109] op_sel_hi:[1,0]
	v_pk_mul_f32 v[20:21], v[20:21], v[108:109] op_sel_hi:[1,0]
	v_mfma_f32_16x16x32_bf16 v[16:19], v[16:19], v[4:7], v[88:91]
	ds_write_b128 v92, v[20:23] offset:17088
	s_nop 1
	v_pk_mul_f32 v[2:3], v[2:3], v[110:111] op_sel_hi:[1,0]
	v_pk_mul_f32 v[0:1], v[0:1], v[110:111] op_sel_hi:[1,0]
	v_mfma_f32_16x16x32_bf16 v[12:15], v[12:15], v[4:7], v[38:41]
	ds_write_b128 v92, v[0:3] offset:25536
	v_cndmask_b32_e32 v0, v33, v34, vcc
	v_cmp_lt_i32_e32 vcc, v36, v35
	v_mfma_f32_16x16x32_bf16 v[8:11], v[8:11], v[4:7], v[56:59]
	v_and_b32_e32 v7, 7, v81
	v_lshlrev_b32_e32 v6, 1, v7
	v_lshlrev_b32_e32 v20, 2, v0
	v_cndmask_b32_e32 v0, v33, v36, vcc
	v_lshlrev_b32_e32 v21, 2, v0
	v_cvt_f32_ubyte0_e32 v0, v6
	v_mul_f32_e32 v0, 0xc1135d8e, v0
	v_mul_f32_e32 v0, 0x3d800000, v0
	v_mul_f32_e32 v1, 0x3fb8aa3b, v0
	v_fma_f32 v2, v0, s35, -v1
	v_rndne_f32_e32 v3, v1
	v_fmac_f32_e32 v2, 0x32a5705f, v0
	v_sub_f32_e32 v1, v1, v3
	v_add_f32_e32 v1, v1, v2
	v_exp_f32_e32 v1, v1
	v_cvt_i32_f32_e32 v2, v3
	v_cmp_lt_i32_e32 vcc, v37, v35
	v_pk_mul_f32 v[10:11], v[10:11], v[110:111] op_sel_hi:[1,0]
	v_pk_mul_f32 v[8:9], v[8:9], v[110:111] op_sel_hi:[1,0]
	v_ldexp_f32 v1, v1, v2
	v_or_b32_e32 v2, 1, v6
	v_cvt_f32_ubyte0_e32 v2, v2
	v_mul_f32_e32 v2, 0xc1135d8e, v2
	v_cndmask_b32_e32 v3, v33, v37, vcc
	v_mul_f32_e32 v2, 0x3d800000, v2
	v_lshlrev_b32_e32 v22, 2, v3
	v_mul_f32_e32 v3, 0x3fb8aa3b, v2
	v_fma_f32 v4, v2, s35, -v3
	v_rndne_f32_e32 v5, v3
	v_fmac_f32_e32 v4, 0x32a5705f, v2
	v_sub_f32_e32 v3, v3, v5
	v_add_f32_e32 v3, v3, v4
	v_exp_f32_e32 v3, v3
	v_cvt_i32_f32_e32 v4, v5
	v_cmp_ngt_f32_e32 vcc, s36, v0
	ds_write_b128 v92, v[8:11] offset:25472
	v_ashrrev_i32_e32 v11, 3, v81
	v_cndmask_b32_e32 v1, 0, v1, vcc
	v_cmp_nlt_f32_e32 vcc, s37, v0
	v_mov_b32_e32 v5, v29
	v_lshlrev_b32_e32 v28, 3, v7
	v_cndmask_b32_e32 v0, v32, v1, vcc
	v_mul_f32_e32 v8, 0.15915494, v0
	v_ldexp_f32 v0, v3, v4
	v_cmp_ngt_f32_e32 vcc, s36, v2
	v_lshlrev_b32_e32 v4, 5, v7
	v_pk_mul_f32 v[18:19], v[18:19], v[110:111] op_sel_hi:[1,0]
	v_cndmask_b32_e32 v0, 0, v0, vcc
	v_cmp_nlt_f32_e32 vcc, s37, v2
	v_pk_mul_f32 v[16:17], v[16:17], v[110:111] op_sel_hi:[1,0]
	v_pk_mul_f32 v[14:15], v[14:15], v[110:111] op_sel_hi:[1,0]
	v_cndmask_b32_e32 v0, v32, v0, vcc
	v_mul_f32_e32 v9, 0.15915494, v0
	v_lshl_add_u64 v[0:1], s[52:53], 0, v[4:5]
	v_mad_u64_u32 v[4:5], s[72:73], v11, s34, v[4:5]
	v_pk_mul_f32 v[12:13], v[12:13], v[110:111] op_sel_hi:[1,0]
	v_lshl_add_u64 v[2:3], s[52:53], 0, v[28:29]
	v_mul_i32_i24_e32 v10, 0xffffffe8, v7
	v_add_u32_e32 v5, s8, v11
	v_lshlrev_b32_e32 v28, 1, v28
	v_lshlrev_b32_e32 v6, 1, v6
	s_mov_b32 s8, 0
	ds_write_b128 v92, v[52:55] offset:192
	ds_write_b128 v92, v[42:45] offset:17024
	ds_write_b128 v92, v[16:19] offset:25344
	ds_write_b128 v92, v[12:15] offset:25408
	s_waitcnt lgkmcnt(0)
	s_barrier

.LBB0_94:
	s_ashr_i32 s4, s65, 31
	s_lshr_b32 s4, s4, 29
	s_add_i32 s4, s65, s4
	s_ashr_i32 s71, s4, 3
	s_and_b32 s4, s4, -8
	s_or_b32 s5, s4, s33
	s_sub_i32 s72, s65, s4
	s_lshl_b32 s73, s5, 7
	s_mul_i32 s4, s5, 5
	s_mul_i32 s5, s72, 3
	s_add_i32 s4, s4, s5
	s_ashr_i32 s5, s4, 31
	s_lshr_b32 s5, s5, 30
	v_mov_b32_e32 v27, v138
	s_add_i32 s5, s4, s5
	s_and_b32 s5, s5, -4
	v_bfe_u32 v4, v27, 3, 3
	v_bitop3_b32 v16, v4, v27, 7 bitop3:0x78
	s_sub_i32 s91, s4, s5
	v_ashrrev_i32_e32 v2, 6, v27
	s_lshl_b32 s6, s91, 6
	v_lshlrev_b32_e32 v83, 3, v16
	v_lshlrev_b32_e32 v34, 12, v2
	v_lshl_or_b32 v2, v2, 5, v4
	v_or_b32_e32 v6, s6, v83
	v_add_u32_e32 v4, s73, v2
	v_ashrrev_i32_e32 v7, 31, v6
	v_mad_i64_i32 v[4:5], s[4:5], v4, s37, v[0:1]
	v_lshlrev_b64 v[12:13], 1, v[6:7]
	v_lshl_add_u64 v[6:7], v[4:5], 0, v[12:13]
	v_readfirstlane_b32 s4, v34
	v_lshl_add_u64 v[6:7], v[6:7], 0, s[12:13]
	s_mov_b32 m0, s4
	v_or_b32_e32 v17, 8, v2
	global_load_lds_dwordx4 v[6:7], off
	v_add_u32_e32 v6, s73, v17
	v_mad_i64_i32 v[6:7], s[86:87], v6, s37, v[0:1]
	v_or_b32_e32 v10, 0x400, v34
	v_lshl_add_u64 v[8:9], v[6:7], 0, v[12:13]
	v_readfirstlane_b32 s14, v10
	v_lshl_add_u64 v[8:9], v[8:9], 0, s[12:13]
	s_mov_b32 m0, s14
	v_or_b32_e32 v18, 16, v2
	global_load_lds_dwordx4 v[8:9], off
	v_add_u32_e32 v8, s73, v18
	v_mad_i64_i32 v[8:9], s[86:87], v8, s37, v[0:1]
	v_or_b32_e32 v14, 0x800, v34
	v_lshl_add_u64 v[10:11], v[8:9], 0, v[12:13]
	v_readfirstlane_b32 s87, v14
	v_lshl_add_u64 v[10:11], v[10:11], 0, s[12:13]
	s_mov_b32 m0, s87
	v_or_b32_e32 v19, 24, v2
	global_load_lds_dwordx4 v[10:11], off
	v_add_u32_e32 v10, s73, v19
	v_mad_i64_i32 v[10:11], s[88:89], v10, s37, v[0:1]
	v_or_b32_e32 v14, 0xc00, v34
	v_lshl_add_u64 v[12:13], v[10:11], 0, v[12:13]
	v_readfirstlane_b32 s90, v14
	s_lshl_b32 s85, s72, 7
	v_lshl_add_u64 v[12:13], v[12:13], 0, s[12:13]
	s_mov_b32 m0, s90
	s_ashr_i32 s7, s6, 31
	global_load_lds_dwordx4 v[12:13], off
	v_add_u32_e32 v12, s85, v2
	v_ashrrev_i32_e32 v13, 31, v12
	v_lshlrev_b64 v[12:13], 9, v[12:13]
	v_add_u32_e32 v28, 0x4000, v34
	v_lshl_add_u64 v[12:13], s[10:11], 0, v[12:13]
	s_lshl_b64 s[6:7], s[6:7], 1
	v_lshl_add_u64 v[14:15], v[12:13], 0, s[6:7]
	v_lshlrev_b32_e32 v2, 4, v16
	v_readfirstlane_b32 s92, v28
	v_lshl_add_u64 v[14:15], v[14:15], 0, v[2:3]
	s_mov_b32 m0, s92
	v_add_u32_e32 v28, 0x4400, v34
	global_load_lds_dwordx4 v[14:15], off
	v_add_u32_e32 v14, s85, v17
	v_ashrrev_i32_e32 v15, 31, v14
	v_lshlrev_b64 v[14:15], 9, v[14:15]
	v_lshl_add_u64 v[14:15], s[10:11], 0, v[14:15]
	v_lshl_add_u64 v[16:17], v[14:15], 0, s[6:7]
	v_readfirstlane_b32 s93, v28
	v_lshl_add_u64 v[16:17], v[16:17], 0, v[2:3]
	s_mov_b32 m0, s93
	s_add_i32 s91, s91, 1
	global_load_lds_dwordx4 v[16:17], off
	v_add_u32_e32 v16, s85, v18
	v_ashrrev_i32_e32 v17, 31, v16
	v_lshlrev_b64 v[16:17], 9, v[16:17]
	v_lshl_add_u64 v[28:29], s[10:11], 0, v[16:17]
	v_add_u32_e32 v18, 0x4800, v34
	v_lshl_add_u64 v[16:17], v[28:29], 0, s[6:7]
	v_readfirstlane_b32 s96, v18
	v_lshl_add_u64 v[16:17], v[16:17], 0, v[2:3]
	s_mov_b32 m0, s96
	v_add_u32_e32 v18, 0x4c00, v34
	global_load_lds_dwordx4 v[16:17], off
	v_add_u32_e32 v16, s85, v19
	v_ashrrev_i32_e32 v17, 31, v16
	v_lshlrev_b64 v[16:17], 9, v[16:17]
	v_lshl_add_u64 v[32:33], s[10:11], 0, v[16:17]
	s_cmp_lg_u32 s91, 4
	v_lshl_add_u64 v[16:17], v[32:33], 0, s[6:7]
	v_readfirstlane_b32 s97, v18
	s_cselect_b32 s98, s91, 0
	v_lshl_add_u64 v[16:17], v[16:17], 0, v[2:3]
	s_mov_b32 m0, s97
	s_lshl_b32 s88, s98, 6
	global_load_lds_dwordx4 v[16:17], off
	v_lshl_add_u64 v[16:17], v[14:15], 0, v[2:3]
	v_lshl_add_u64 v[14:15], v[28:29], 0, v[2:3]
	v_or_b32_e32 v28, s88, v83
	v_ashrrev_i32_e32 v29, 31, v28
	v_add_u32_e32 v35, 0x8000, v34
	v_lshlrev_b64 v[28:29], 1, v[28:29]
	v_lshl_add_u64 v[18:19], v[12:13], 0, v[2:3]
	v_lshl_add_u64 v[12:13], v[32:33], 0, v[2:3]
	v_lshl_add_u64 v[32:33], v[4:5], 0, v[28:29]
	v_readfirstlane_b32 s5, v35
	v_lshl_add_u64 v[32:33], v[32:33], 0, s[12:13]
	s_mov_b32 m0, s5
	v_add_u32_e32 v35, 0x8400, v34
	s_waitcnt vmcnt(0) lgkmcnt(0)
	s_barrier
	global_load_lds_dwordx4 v[32:33], off
	v_lshl_add_u64 v[32:33], v[6:7], 0, v[28:29]
	v_readfirstlane_b32 s6, v35
	v_lshl_add_u64 v[32:33], v[32:33], 0, s[12:13]
	s_mov_b32 m0, s6
	v_add_u32_e32 v35, 0x8800, v34
	global_load_lds_dwordx4 v[32:33], off
	v_lshl_add_u64 v[32:33], v[8:9], 0, v[28:29]
	v_readfirstlane_b32 s7, v35
	v_lshl_add_u64 v[32:33], v[32:33], 0, s[12:13]
	s_mov_b32 m0, s7
	v_lshl_add_u64 v[28:29], v[10:11], 0, v[28:29]
	global_load_lds_dwordx4 v[32:33], off
	v_add_u32_e32 v32, 0x8c00, v34
	s_ashr_i32 s89, s88, 31
	v_readfirstlane_b32 s85, v32
	v_add_u32_e32 v32, 0xc000, v34
	v_lshl_add_u64 v[28:29], v[28:29], 0, s[12:13]
	s_mov_b32 m0, s85
	s_lshl_b64 s[94:95], s[88:89], 1
	v_readfirstlane_b32 s86, v32
	v_add_u32_e32 v32, 0xc400, v34
	global_load_lds_dwordx4 v[28:29], off
	v_lshl_add_u64 v[28:29], v[18:19], 0, s[94:95]
	s_mov_b32 m0, s86
	v_readfirstlane_b32 s88, v32
	v_add_u32_e32 v32, 0xc800, v34
	global_load_lds_dwordx4 v[28:29], off
	v_lshl_add_u64 v[28:29], v[16:17], 0, s[94:95]
	s_mov_b32 m0, s88
	v_readfirstlane_b32 s89, v32
	v_add_u32_e32 v32, 0xcc00, v34
	global_load_lds_dwordx4 v[28:29], off
	v_lshl_add_u64 v[28:29], v[14:15], 0, s[94:95]
	s_mov_b32 m0, s89
	v_readfirstlane_b32 s91, v32
	v_bfe_u32 v31, v27, 4, 2
	global_load_lds_dwordx4 v[28:29], off
	v_lshl_add_u64 v[28:29], v[12:13], 0, s[94:95]
	s_mov_b32 m0, s91
	v_and_b32_e32 v26, 15, v27
	v_bitop3_b32 v2, v31, v27, 7 bitop3:0x78
	global_load_lds_dwordx4 v[28:29], off
	s_setprio 1
	v_lshlrev_b32_e32 v29, 7, v27
	v_ashrrev_i32_e32 v25, 7, v27
	v_lshlrev_b32_e32 v2, 4, v2
	v_lshlrev_b32_e32 v28, 7, v26
	v_and_b32_e32 v29, 0x2780, v29
	v_or_b32_e32 v124, v2, v29
	v_lshl_or_b32 v28, v25, 13, v28
	ds_read_b128 v[32:35], v124 offset:16384
	v_or_b32_e32 v125, v2, v28
	ds_read_b128 v[36:39], v124 offset:18432
	ds_read_b128 v[40:43], v125
	ds_read_b128 v[44:47], v125 offset:2048
	ds_read_b128 v[52:55], v124 offset:20480
	ds_read_b128 v[60:63], v124 offset:22528
	ds_read_b128 v[84:87], v125 offset:4096
	ds_read_b128 v[88:91], v125 offset:6144
	v_and_b32_e32 v2, 7, v27
	v_bitop3_b32 v2, v31, v2, 4 bitop3:0x36
	v_lshlrev_b32_e32 v2, 4, v2
	v_or_b32_e32 v27, v2, v29
	s_waitcnt lgkmcnt(0)
	v_mfma_f32_16x16x32_bf16 v[48:51], v[32:35], v[40:43], 0
	ds_read_b128 v[104:107], v27 offset:16384
	v_or_b32_e32 v31, v2, v28
	s_add_i32 s98, s98, 1
	v_mfma_f32_16x16x32_bf16 v[56:59], v[36:39], v[40:43], 0
	s_cmp_lg_u32 s98, 4
	s_cselect_b32 s98, s98, 0
	s_lshl_b32 s94, s98, 6
	v_mfma_f32_16x16x32_bf16 v[64:67], v[52:55], v[40:43], 0
	v_or_b32_e32 v28, s94, v83
	v_ashrrev_i32_e32 v29, 31, v28
	v_lshlrev_b64 v[28:29], 1, v[28:29]
	v_mfma_f32_16x16x32_bf16 v[40:43], v[60:63], v[40:43], 0
	v_lshl_add_u64 v[80:81], v[4:5], 0, v[28:29]
	v_lshl_add_u64 v[80:81], v[80:81], 0, s[12:13]
	s_mov_b32 m0, s4
	v_mfma_f32_16x16x32_bf16 v[68:71], v[32:35], v[44:47], 0
	s_ashr_i32 s95, s94, 31
	s_lshl_b64 s[94:95], s[94:95], 1
	s_add_i32 s98, s98, 1
	v_mfma_f32_16x16x32_bf16 v[72:75], v[36:39], v[44:47], 0
	s_lshl_b32 s4, s98, 6
	s_cmp_lg_u32 s98, 4
	s_cselect_b32 s4, s4, 0
	v_mfma_f32_16x16x32_bf16 v[76:79], v[52:55], v[44:47], 0
	v_or_b32_e32 v2, s4, v83
	v_lshlrev_b32_e32 v2, 1, v2
	v_lshl_add_u64 v[4:5], v[4:5], 0, v[2:3]
	v_mfma_f32_16x16x32_bf16 v[44:47], v[60:63], v[44:47], 0
	v_lshl_add_u64 v[4:5], v[4:5], 0, s[12:13]
	v_mfma_f32_16x16x32_bf16 v[92:95], v[32:35], v[84:87], 0
	v_mfma_f32_16x16x32_bf16 v[96:99], v[36:39], v[84:87], 0
	v_mfma_f32_16x16x32_bf16 v[100:103], v[52:55], v[84:87], 0
	v_mfma_f32_16x16x32_bf16 v[84:87], v[60:63], v[84:87], 0
	v_mfma_f32_16x16x32_bf16 v[32:35], v[32:35], v[88:91], 0
	v_mfma_f32_16x16x32_bf16 v[36:39], v[36:39], v[88:91], 0
	v_mfma_f32_16x16x32_bf16 v[52:55], v[52:55], v[88:91], 0
	v_mfma_f32_16x16x32_bf16 v[60:63], v[60:63], v[88:91], 0
	ds_read_b128 v[88:91], v27 offset:18432
	ds_read_b128 v[108:111], v31
	ds_read_b128 v[112:115], v31 offset:2048
	ds_read_b128 v[116:119], v27 offset:20480
	ds_read_b128 v[120:123], v27 offset:22528
	s_waitcnt lgkmcnt(3)
	v_mfma_f32_16x16x32_bf16 v[48:51], v[104:107], v[108:111], v[48:51]
	v_mfma_f32_16x16x32_bf16 v[56:59], v[88:91], v[108:111], v[56:59]
	s_waitcnt lgkmcnt(1)
	v_mfma_f32_16x16x32_bf16 v[64:67], v[116:119], v[108:111], v[64:67]
	s_waitcnt lgkmcnt(0)
	v_mfma_f32_16x16x32_bf16 v[40:43], v[120:123], v[108:111], v[40:43]
	v_mfma_f32_16x16x32_bf16 v[68:71], v[104:107], v[112:115], v[68:71]
	v_mfma_f32_16x16x32_bf16 v[72:75], v[88:91], v[112:115], v[72:75]
	v_mfma_f32_16x16x32_bf16 v[76:79], v[116:119], v[112:115], v[76:79]
	v_mfma_f32_16x16x32_bf16 v[44:47], v[120:123], v[112:115], v[44:47]
	ds_read_b128 v[108:111], v31 offset:4096
	ds_read_b128 v[112:115], v31 offset:6144
	s_setprio 0
	s_waitcnt vmcnt(0) lgkmcnt(0)
	s_barrier
	global_load_lds_dwordx4 v[80:81], off
	v_lshl_add_u64 v[80:81], v[6:7], 0, v[28:29]
	v_lshl_add_u64 v[80:81], v[80:81], 0, s[12:13]
	s_mov_b32 m0, s14
	v_mfma_f32_16x16x32_bf16 v[92:95], v[104:107], v[108:111], v[92:95]
	global_load_lds_dwordx4 v[80:81], off
	v_lshl_add_u64 v[80:81], v[8:9], 0, v[28:29]
	v_lshl_add_u64 v[80:81], v[80:81], 0, s[12:13]
	s_mov_b32 m0, s87
	v_lshl_add_u64 v[28:29], v[10:11], 0, v[28:29]
	global_load_lds_dwordx4 v[80:81], off
	v_lshl_add_u64 v[28:29], v[28:29], 0, s[12:13]
	s_mov_b32 m0, s90
	v_mfma_f32_16x16x32_bf16 v[96:99], v[88:91], v[108:111], v[96:99]
	global_load_lds_dwordx4 v[28:29], off
	v_lshl_add_u64 v[28:29], v[18:19], 0, s[94:95]
	s_mov_b32 m0, s92
	v_mfma_f32_16x16x32_bf16 v[100:103], v[116:119], v[108:111], v[100:103]
	global_load_lds_dwordx4 v[28:29], off
	v_lshl_add_u64 v[28:29], v[16:17], 0, s[94:95]
	s_mov_b32 m0, s93
	v_mfma_f32_16x16x32_bf16 v[84:87], v[120:123], v[108:111], v[84:87]
	global_load_lds_dwordx4 v[28:29], off
	v_lshl_add_u64 v[28:29], v[14:15], 0, s[94:95]
	s_mov_b32 m0, s96
	v_mfma_f32_16x16x32_bf16 v[32:35], v[104:107], v[112:115], v[32:35]
	global_load_lds_dwordx4 v[28:29], off
	v_lshl_add_u64 v[28:29], v[12:13], 0, s[94:95]
	s_mov_b32 m0, s97
	v_mfma_f32_16x16x32_bf16 v[36:39], v[88:91], v[112:115], v[36:39]
	global_load_lds_dwordx4 v[28:29], off
	s_setprio 1
	ds_read_b128 v[88:91], v124 offset:49152
	v_mfma_f32_16x16x32_bf16 v[52:55], v[116:119], v[112:115], v[52:55]
	s_mov_b32 m0, s5
	s_lshl_b32 s14, s4, 1
	v_mfma_f32_16x16x32_bf16 v[60:63], v[120:123], v[112:115], v[60:63]
	ds_read_b128 v[104:107], v124 offset:51200
	ds_read_b128 v[108:111], v125 offset:32768
	ds_read_b128 v[112:115], v125 offset:34816
	ds_read_b128 v[116:119], v124 offset:53248
	ds_read_b128 v[120:123], v124 offset:55296
	s_waitcnt lgkmcnt(0)
	v_mfma_f32_16x16x32_bf16 v[48:51], v[88:91], v[108:111], v[48:51]
	v_mfma_f32_16x16x32_bf16 v[56:59], v[104:107], v[108:111], v[56:59]
	v_mfma_f32_16x16x32_bf16 v[64:67], v[116:119], v[108:111], v[64:67]
	v_mfma_f32_16x16x32_bf16 v[40:43], v[120:123], v[108:111], v[40:43]
	v_mfma_f32_16x16x32_bf16 v[68:71], v[88:91], v[112:115], v[68:71]
	v_mfma_f32_16x16x32_bf16 v[72:75], v[104:107], v[112:115], v[72:75]
	v_mfma_f32_16x16x32_bf16 v[76:79], v[116:119], v[112:115], v[76:79]
	v_mfma_f32_16x16x32_bf16 v[44:47], v[120:123], v[112:115], v[44:47]
	ds_read_b128 v[108:111], v125 offset:36864
	ds_read_b128 v[112:115], v125 offset:38912
	s_waitcnt lgkmcnt(1)
	v_mfma_f32_16x16x32_bf16 v[92:95], v[88:91], v[108:111], v[92:95]
	v_mfma_f32_16x16x32_bf16 v[96:99], v[104:107], v[108:111], v[96:99]
	v_mfma_f32_16x16x32_bf16 v[100:103], v[116:119], v[108:111], v[100:103]
	v_mfma_f32_16x16x32_bf16 v[84:87], v[120:123], v[108:111], v[84:87]
	s_waitcnt lgkmcnt(0)
	v_mfma_f32_16x16x32_bf16 v[32:35], v[88:91], v[112:115], v[32:35]
	ds_read_b128 v[88:91], v27 offset:49152
	v_mfma_f32_16x16x32_bf16 v[36:39], v[104:107], v[112:115], v[36:39]
	v_mfma_f32_16x16x32_bf16 v[52:55], v[116:119], v[112:115], v[52:55]
	v_mfma_f32_16x16x32_bf16 v[60:63], v[120:123], v[112:115], v[60:63]
	ds_read_b128 v[104:107], v27 offset:51200
	ds_read_b128 v[108:111], v31 offset:32768
	ds_read_b128 v[112:115], v31 offset:34816
	ds_read_b128 v[116:119], v27 offset:53248
	ds_read_b128 v[120:123], v27 offset:55296
	s_waitcnt lgkmcnt(3)
	v_mfma_f32_16x16x32_bf16 v[48:51], v[88:91], v[108:111], v[48:51]
	v_mfma_f32_16x16x32_bf16 v[56:59], v[104:107], v[108:111], v[56:59]
	s_waitcnt lgkmcnt(1)
	v_mfma_f32_16x16x32_bf16 v[64:67], v[116:119], v[108:111], v[64:67]
	s_waitcnt lgkmcnt(0)
	v_mfma_f32_16x16x32_bf16 v[40:43], v[120:123], v[108:111], v[40:43]
	v_mfma_f32_16x16x32_bf16 v[68:71], v[88:91], v[112:115], v[68:71]
	v_mfma_f32_16x16x32_bf16 v[72:75], v[104:107], v[112:115], v[72:75]
	v_mfma_f32_16x16x32_bf16 v[76:79], v[116:119], v[112:115], v[76:79]
	v_mfma_f32_16x16x32_bf16 v[44:47], v[120:123], v[112:115], v[44:47]
	ds_read_b128 v[108:111], v31 offset:36864
	ds_read_b128 v[112:115], v31 offset:38912
	s_setprio 0
	s_waitcnt vmcnt(0) lgkmcnt(0)
	s_barrier
	global_load_lds_dwordx4 v[4:5], off
	v_lshl_add_u64 v[4:5], v[6:7], 0, v[2:3]
	v_lshl_add_u64 v[4:5], v[4:5], 0, s[12:13]
	s_mov_b32 m0, s6
	v_mfma_f32_16x16x32_bf16 v[92:95], v[88:91], v[108:111], v[92:95]
	global_load_lds_dwordx4 v[4:5], off
	v_lshl_add_u64 v[4:5], v[8:9], 0, v[2:3]
	v_lshl_add_u64 v[4:5], v[4:5], 0, s[12:13]
	s_mov_b32 m0, s7
	v_mfma_f32_16x16x32_bf16 v[96:99], v[104:107], v[108:111], v[96:99]
	global_load_lds_dwordx4 v[4:5], off
	v_lshl_add_u64 v[4:5], v[10:11], 0, v[2:3]
	v_lshl_add_u64 v[4:5], v[4:5], 0, s[12:13]
	s_mov_b32 m0, s85
	v_mfma_f32_16x16x32_bf16 v[32:35], v[88:91], v[112:115], v[32:35]
	global_load_lds_dwordx4 v[4:5], off
	v_lshl_add_u64 v[4:5], v[18:19], 0, s[14:15]
	s_mov_b32 m0, s86
	v_mfma_f32_16x16x32_bf16 v[36:39], v[104:107], v[112:115], v[36:39]
	global_load_lds_dwordx4 v[4:5], off
	v_lshl_add_u64 v[4:5], v[16:17], 0, s[14:15]
	s_mov_b32 m0, s88
	v_mfma_f32_16x16x32_bf16 v[8:11], v[120:123], v[112:115], v[60:63]
	global_load_lds_dwordx4 v[4:5], off
	v_lshl_add_u64 v[4:5], v[14:15], 0, s[14:15]
	s_mov_b32 m0, s89
	v_mfma_f32_16x16x32_bf16 v[100:103], v[116:119], v[108:111], v[100:103]
	global_load_lds_dwordx4 v[4:5], off
	v_lshl_add_u64 v[4:5], v[12:13], 0, s[14:15]
	s_mov_b32 m0, s91
	v_mfma_f32_16x16x32_bf16 v[84:87], v[120:123], v[108:111], v[84:87]
	global_load_lds_dwordx4 v[4:5], off
	s_setprio 1
	ds_read_b128 v[4:7], v124 offset:16384
	ds_read_b128 v[12:15], v124 offset:18432
	ds_read_b128 v[16:19], v125
	ds_read_b128 v[60:63], v125 offset:2048
	ds_read_b128 v[88:91], v124 offset:20480
	ds_read_b128 v[104:107], v124 offset:22528
	s_waitcnt lgkmcnt(0)
	v_mfma_f32_16x16x32_bf16 v[48:51], v[4:7], v[16:19], v[48:51]
	v_lshl_add_u32 v2, v25, 6, s73
	v_or_b32_e32 v26, v2, v26
	v_mfma_f32_16x16x32_bf16 v[56:59], v[12:15], v[16:19], v[56:59]
	v_mfma_f32_16x16x32_bf16 v[64:67], v[88:91], v[16:19], v[64:67]
	v_mfma_f32_16x16x32_bf16 v[16:19], v[104:107], v[16:19], v[40:43]
	v_mfma_f32_16x16x32_bf16 v[40:43], v[4:7], v[60:63], v[68:71]
	v_mfma_f32_16x16x32_bf16 v[68:71], v[12:15], v[60:63], v[72:75]
	v_mfma_f32_16x16x32_bf16 v[72:75], v[88:91], v[60:63], v[76:79]
	v_mfma_f32_16x16x32_bf16 v[44:47], v[104:107], v[60:63], v[44:47]
	ds_read_b128 v[60:63], v125 offset:4096
	s_nop 0
	ds_read_b128 v[76:79], v125 offset:6144
	v_mfma_f32_16x16x32_bf16 v[52:55], v[116:119], v[112:115], v[52:55]
	s_waitcnt lgkmcnt(1)
	v_mfma_f32_16x16x32_bf16 v[92:95], v[4:7], v[60:63], v[92:95]
	v_mfma_f32_16x16x32_bf16 v[96:99], v[12:15], v[60:63], v[96:99]
	v_mfma_f32_16x16x32_bf16 v[100:103], v[88:91], v[60:63], v[100:103]
	v_mfma_f32_16x16x32_bf16 v[60:63], v[104:107], v[60:63], v[84:87]
	s_waitcnt lgkmcnt(0)
	v_mfma_f32_16x16x32_bf16 v[4:7], v[4:7], v[76:79], v[32:35]
	v_mfma_f32_16x16x32_bf16 v[12:15], v[12:15], v[76:79], v[36:39]
	v_mfma_f32_16x16x32_bf16 v[32:35], v[88:91], v[76:79], v[52:55]
	s_nop 1
	ds_read_b128 v[36:39], v27 offset:16384
	v_mfma_f32_16x16x32_bf16 v[8:11], v[104:107], v[76:79], v[8:11]
	ds_read_b128 v[52:55], v27 offset:18432
	ds_read_b128 v[76:79], v31
	ds_read_b128 v[84:87], v31 offset:2048
	ds_read_b128 v[88:91], v27 offset:20480
	ds_read_b128 v[104:107], v27 offset:22528
	s_waitcnt lgkmcnt(3)
	v_mfma_f32_16x16x32_bf16 v[48:51], v[36:39], v[76:79], v[48:51]
	v_mfma_f32_16x16x32_bf16 v[56:59], v[52:55], v[76:79], v[56:59]
	s_waitcnt lgkmcnt(1)
	v_mfma_f32_16x16x32_bf16 v[64:67], v[88:91], v[76:79], v[64:67]
	s_waitcnt lgkmcnt(0)
	v_mfma_f32_16x16x32_bf16 v[16:19], v[104:107], v[76:79], v[16:19]
	v_mfma_f32_16x16x32_bf16 v[40:43], v[36:39], v[84:87], v[40:43]
	v_mfma_f32_16x16x32_bf16 v[68:71], v[52:55], v[84:87], v[68:71]
	v_mfma_f32_16x16x32_bf16 v[72:75], v[88:91], v[84:87], v[72:75]
	v_mfma_f32_16x16x32_bf16 v[44:47], v[104:107], v[84:87], v[44:47]
	ds_read_b128 v[76:79], v31 offset:4096
	ds_read_b128 v[84:87], v31 offset:6144
	s_setprio 0
	s_waitcnt vmcnt(0) lgkmcnt(0)
	s_barrier
	v_mfma_f32_16x16x32_bf16 v[92:95], v[36:39], v[76:79], v[92:95]
	v_mfma_f32_16x16x32_bf16 v[96:99], v[52:55], v[76:79], v[96:99]
	v_mfma_f32_16x16x32_bf16 v[100:103], v[88:91], v[76:79], v[100:103]
	v_mfma_f32_16x16x32_bf16 v[60:63], v[104:107], v[76:79], v[60:63]
	ds_read_b128 v[76:79], v124 offset:51200
	v_mfma_f32_16x16x32_bf16 v[4:7], v[36:39], v[84:87], v[4:7]
	ds_read_b128 v[36:39], v124 offset:49152
	v_mfma_f32_16x16x32_bf16 v[12:15], v[52:55], v[84:87], v[12:15]
	ds_read_b128 v[52:55], v125 offset:32768
	v_mfma_f32_16x16x32_bf16 v[32:35], v[88:91], v[84:87], v[32:35]
	ds_read_b128 v[88:91], v124 offset:55296
	v_mfma_f32_16x16x32_bf16 v[8:11], v[104:107], v[84:87], v[8:11]
	ds_read_b128 v[84:87], v124 offset:53248
	ds_read_b128 v[104:107], v31 offset:38912
	s_waitcnt lgkmcnt(3)
	v_mfma_f32_16x16x32_bf16 v[48:51], v[36:39], v[52:55], v[48:51]
	v_mfma_f32_16x16x32_bf16 v[56:59], v[76:79], v[52:55], v[56:59]
	s_waitcnt lgkmcnt(1)
	v_mfma_f32_16x16x32_bf16 v[64:67], v[84:87], v[52:55], v[64:67]
	v_mfma_f32_16x16x32_bf16 v[16:19], v[88:91], v[52:55], v[16:19]
	ds_read_b128 v[52:55], v125 offset:34816
	s_waitcnt lgkmcnt(0)
	v_mfma_f32_16x16x32_bf16 v[40:43], v[36:39], v[52:55], v[40:43]
	v_mfma_f32_16x16x32_bf16 v[68:71], v[76:79], v[52:55], v[68:71]
	v_mfma_f32_16x16x32_bf16 v[72:75], v[84:87], v[52:55], v[72:75]
	v_mfma_f32_16x16x32_bf16 v[44:47], v[88:91], v[52:55], v[44:47]
	ds_read_b128 v[52:55], v125 offset:36864
	s_waitcnt lgkmcnt(0)
	v_mfma_f32_16x16x32_bf16 v[92:95], v[36:39], v[52:55], v[92:95]
	v_mfma_f32_16x16x32_bf16 v[96:99], v[76:79], v[52:55], v[96:99]
	v_mfma_f32_16x16x32_bf16 v[100:103], v[84:87], v[52:55], v[100:103]
	v_mfma_f32_16x16x32_bf16 v[52:55], v[88:91], v[52:55], v[60:63]
	s_nop 2
	ds_read_b128 v[60:63], v125 offset:38912
	s_waitcnt lgkmcnt(0)
	v_mfma_f32_16x16x32_bf16 v[4:7], v[36:39], v[60:63], v[4:7]
	ds_read_b128 v[36:39], v27 offset:49152
	v_mfma_f32_16x16x32_bf16 v[12:15], v[76:79], v[60:63], v[12:15]
	ds_read_b128 v[76:79], v27 offset:51200
	v_mfma_f32_16x16x32_bf16 v[32:35], v[84:87], v[60:63], v[32:35]
	ds_read_b128 v[84:87], v27 offset:53248
	v_mfma_f32_16x16x32_bf16 v[8:11], v[88:91], v[60:63], v[8:11]
	ds_read_b128 v[88:91], v27 offset:55296
	ds_read_b128 v[60:63], v31 offset:32768
	v_ashrrev_i32_e32 v27, 31, v26
	s_waitcnt lgkmcnt(0)
	v_mfma_f32_16x16x32_bf16 v[48:51], v[36:39], v[60:63], v[48:51]
	v_lshl_add_u64 v[80:81], v[26:27], 2, s[8:9]
	v_mfma_f32_16x16x32_bf16 v[56:59], v[76:79], v[60:63], v[56:59]
	v_mfma_f32_16x16x32_bf16 v[64:67], v[84:87], v[60:63], v[64:67]
	v_mfma_f32_16x16x32_bf16 v[16:19], v[88:91], v[60:63], v[16:19]
	ds_read_b128 v[60:63], v31 offset:34816
	s_waitcnt lgkmcnt(0)
	v_mfma_f32_16x16x32_bf16 v[40:43], v[36:39], v[60:63], v[40:43]
	v_mfma_f32_16x16x32_bf16 v[68:71], v[76:79], v[60:63], v[68:71]
	v_mfma_f32_16x16x32_bf16 v[72:75], v[84:87], v[60:63], v[72:75]
	v_mfma_f32_16x16x32_bf16 v[44:47], v[88:91], v[60:63], v[44:47]
	ds_read_b128 v[60:63], v31 offset:36864
	s_waitcnt lgkmcnt(0)
	s_barrier
	global_load_dword v2, v[80:81], off
	global_load_dword v25, v[80:81], off offset:64
	global_load_dword v31, v[80:81], off offset:128
	v_mfma_f32_16x16x32_bf16 v[92:95], v[36:39], v[60:63], v[92:95]
	v_mfma_f32_16x16x32_bf16 v[96:99], v[76:79], v[60:63], v[96:99]
	v_mfma_f32_16x16x32_bf16 v[26:29], v[84:87], v[60:63], v[100:103]
	v_mfma_f32_16x16x32_bf16 v[52:55], v[88:91], v[60:63], v[52:55]
	global_load_dword v60, v[80:81], off offset:192
	s_waitcnt vmcnt(3)
	v_fmamk_f32 v2, v2, 0x3b800000, v23
	v_mul_f32_e32 v61, 0x4b800000, v2
	v_cmp_gt_f32_e32 vcc, s38, v2
	v_mfma_f32_16x16x32_bf16 v[4:7], v[36:39], v[104:107], v[4:7]
	s_nop 0
	v_cndmask_b32_e32 v2, v2, v61, vcc
	v_rsq_f32_e32 v2, v2
	v_mfma_f32_16x16x32_bf16 v[36:39], v[76:79], v[104:107], v[12:15]
	s_waitcnt vmcnt(2)
	s_nop 1
	v_fmamk_f32 v12, v25, 0x3b800000, v23
	v_mul_f32_e32 v13, 0x4b800000, v12
	v_cmp_gt_f32_e64 s[4:5], s38, v12
	s_waitcnt vmcnt(1)
	v_fmamk_f32 v14, v31, 0x3b800000, v23
	v_mul_f32_e32 v15, 0x4b800000, v14
	v_cndmask_b32_e64 v12, v12, v13, s[4:5]
	v_mul_f32_e32 v13, 0x45800000, v2
	v_cndmask_b32_e32 v2, v2, v13, vcc
	v_cmp_gt_f32_e32 vcc, s38, v14
	v_rsq_f32_e32 v12, v12
	v_mfma_f32_16x16x32_bf16 v[32:35], v[84:87], v[104:107], v[32:35]
	v_cndmask_b32_e32 v14, v14, v15, vcc
	s_waitcnt vmcnt(0)
	v_fmamk_f32 v15, v60, 0x3b800000, v23
	v_mul_f32_e32 v25, 0x4b800000, v15
	v_cmp_gt_f32_e64 s[6:7], s38, v15
	v_rsq_f32_e32 v14, v14
	v_mul_f32_e32 v13, 0x45800000, v12
	v_cndmask_b32_e64 v15, v15, v25, s[6:7]
	v_rsq_f32_e32 v15, v15
	v_cndmask_b32_e64 v12, v12, v13, s[4:5]
	v_mul_f32_e32 v13, 0x45800000, v14
	v_cndmask_b32_e32 v60, v14, v13, vcc
	v_mul_f32_e32 v13, 0x45800000, v15
	v_mov_b32_e32 v14, v138
	v_cndmask_b32_e64 v62, v15, v13, s[6:7]
	v_mfma_f32_16x16x32_bf16 v[8:11], v[88:91], v[104:107], v[8:11]
	v_and_b32_e32 v15, 15, v14
	v_lshrrev_b32_e32 v25, 1, v14
	v_and_b32_e32 v13, 64, v14
	v_and_or_b32 v15, v25, s39, v15
	v_and_b32_e32 v25, 48, v14
	v_lshl_or_b32 v76, v13, 2, v25
	v_mad_u64_u32 v[76:77], s[4:5], v15, s50, v[76:77]
	v_pk_mul_f32 v[18:19], v[18:19], v[2:3] op_sel_hi:[1,0]
	v_pk_mul_f32 v[16:17], v[16:17], v[2:3] op_sel_hi:[1,0]
	v_pk_mul_f32 v[6:7], v[6:7], v[62:63] op_sel_hi:[1,0]
	v_pk_mul_f32 v[4:5], v[4:5], v[62:63] op_sel_hi:[1,0]
	ds_write_b128 v76, v[16:19] offset:192
	v_pk_mul_f32 v[18:19], v[42:43], v[12:13] op_sel_hi:[1,0]
	v_pk_mul_f32 v[16:17], v[40:41], v[12:13] op_sel_hi:[1,0]
	ds_write_b128 v76, v[4:7] offset:25344
	v_pk_mul_f32 v[6:7], v[38:39], v[62:63] op_sel_hi:[1,0]
	v_pk_mul_f32 v[4:5], v[36:37], v[62:63] op_sel_hi:[1,0]
	ds_write_b128 v76, v[16:19] offset:8448
	v_pk_mul_f32 v[18:19], v[70:71], v[12:13] op_sel_hi:[1,0]
	v_pk_mul_f32 v[16:17], v[68:69], v[12:13] op_sel_hi:[1,0]
	ds_write_b128 v76, v[4:7] offset:25408
	v_pk_mul_f32 v[6:7], v[34:35], v[62:63] op_sel_hi:[1,0]
	v_pk_mul_f32 v[4:5], v[32:33], v[62:63] op_sel_hi:[1,0]
	v_pk_mul_f32 v[50:51], v[50:51], v[2:3] op_sel_hi:[1,0]
	v_pk_mul_f32 v[48:49], v[48:49], v[2:3] op_sel_hi:[1,0]
	ds_write_b128 v76, v[16:19] offset:8512
	v_pk_mul_f32 v[18:19], v[74:75], v[12:13] op_sel_hi:[1,0]
	v_pk_mul_f32 v[16:17], v[72:73], v[12:13] op_sel_hi:[1,0]
	ds_write_b128 v76, v[4:7] offset:25472
	v_pk_mul_f32 v[4:5], v[8:9], v[62:63] op_sel_hi:[1,0]
	v_and_b32_e32 v8, 7, v14
	ds_write_b128 v76, v[48:51]
	v_pk_mul_f32 v[50:51], v[58:59], v[2:3] op_sel_hi:[1,0]
	v_pk_mul_f32 v[48:49], v[56:57], v[2:3] op_sel_hi:[1,0]
	ds_write_b128 v76, v[16:19] offset:8576
	v_pk_mul_f32 v[18:19], v[46:47], v[12:13] op_sel_hi:[1,0]
	v_pk_mul_f32 v[16:17], v[44:45], v[12:13] op_sel_hi:[1,0]
	v_lshlrev_b32_e32 v12, 1, v8
	ds_write_b128 v76, v[48:51] offset:64
	v_pk_mul_f32 v[50:51], v[66:67], v[2:3] op_sel_hi:[1,0]
	v_pk_mul_f32 v[48:49], v[64:65], v[2:3] op_sel_hi:[1,0]
	v_cvt_f32_ubyte0_e32 v2, v12
	v_pk_mul_f32 v[6:7], v[10:11], v[62:63] op_sel_hi:[1,0]
	v_mul_f32_e32 v2, 0xc1135d8e, v2
	ds_write_b128 v76, v[4:7] offset:25536
	v_mul_f32_e32 v4, 0x3d800000, v2
	v_mul_f32_e32 v2, 0x3fb8aa3b, v4
	v_fma_f32 v5, v4, s51, -v2
	v_rndne_f32_e32 v6, v2
	v_fmac_f32_e32 v5, 0x32a5705f, v4
	v_sub_f32_e32 v2, v2, v6
	v_add_f32_e32 v2, v2, v5
	v_exp_f32_e32 v5, v2
	v_cvt_i32_f32_e32 v6, v6
	v_cmp_ngt_f32_e32 vcc, s52, v4
	ds_write_b128 v76, v[16:19] offset:8640
	v_pk_mul_f32 v[18:19], v[94:95], v[60:61] op_sel_hi:[1,0]
	v_ldexp_f32 v5, v5, v6
	v_or_b32_e32 v6, 1, v12
	v_cvt_f32_ubyte0_e32 v6, v6
	v_mul_f32_e32 v6, 0xc1135d8e, v6
	v_mul_f32_e32 v6, 0x3d800000, v6
	v_mul_f32_e32 v7, 0x3fb8aa3b, v6
	v_fma_f32 v9, v6, s51, -v7
	v_rndne_f32_e32 v10, v7
	v_fmac_f32_e32 v9, 0x32a5705f, v6
	v_sub_f32_e32 v7, v7, v10
	v_add_f32_e32 v7, v7, v9
	v_exp_f32_e32 v7, v7
	v_cvt_i32_f32_e32 v9, v10
	v_cndmask_b32_e32 v5, 0, v5, vcc
	v_cmp_nlt_f32_e32 vcc, s53, v4
	v_pk_mul_f32 v[16:17], v[92:93], v[60:61] op_sel_hi:[1,0]
	ds_write_b128 v76, v[16:19] offset:16896
	v_cndmask_b32_e32 v4, v24, v5, vcc
	v_pk_mul_f32 v[18:19], v[98:99], v[60:61] op_sel_hi:[1,0]
	v_pk_mul_f32 v[16:17], v[96:97], v[60:61] op_sel_hi:[1,0]
	s_mul_i32 s4, s72, 0x60
	v_mul_f32_e32 v15, 0.15915494, v4
	v_ldexp_f32 v4, v7, v9
	v_cmp_ngt_f32_e32 vcc, s52, v6
	ds_write_b128 v76, v[16:19] offset:16960
	v_pk_mul_f32 v[18:19], v[28:29], v[60:61] op_sel_hi:[1,0]
	v_pk_mul_f32 v[16:17], v[26:27], v[60:61] op_sel_hi:[1,0]
	s_ashr_i32 s5, s4, 31
	v_cndmask_b32_e32 v4, 0, v4, vcc
	v_cmp_nlt_f32_e32 vcc, s53, v6
	ds_write_b128 v76, v[16:19] offset:17024
	v_pk_mul_f32 v[18:19], v[54:55], v[60:61] op_sel_hi:[1,0]
	v_pk_mul_f32 v[16:17], v[52:53], v[60:61] op_sel_hi:[1,0]
	v_ashrrev_i32_e32 v13, 3, v14
	v_cndmask_b32_e32 v4, v24, v4, vcc
	v_lshlrev_b32_e32 v10, 5, v8
	v_mov_b32_e32 v11, v3
	s_lshl_b64 s[4:5], s[4:5], 1
	ds_write_b128 v76, v[16:19] offset:17088
	v_mul_f32_e32 v16, 0.15915494, v4
	v_lshl_add_u64 v[4:5], s[54:55], 0, v[10:11]
	s_add_u32 s4, s31, s4
	v_mad_u64_u32 v[10:11], s[6:7], v13, s50, v[10:11]
	s_addc_u32 s5, s34, s5
	s_lshl_b32 s6, s71, 10
	v_lshlrev_b32_e32 v2, 3, v8
	v_lshlrev_b32_e32 v8, 2, v8
	v_mov_b32_e32 v9, v3
	s_or_b32 s6, s6, s30
	v_lshl_add_u64 v[6:7], s[54:55], 0, v[2:3]
	v_lshl_add_u64 v[8:9], s[80:81], 0, v[8:9]
	v_add_u32_e32 v11, s6, v13
	v_lshlrev_b32_e32 v2, 1, v2
	v_lshlrev_b32_e32 v12, 1, v12
	s_mov_b32 s6, 0
	ds_write_b128 v76, v[48:51] offset:128
	s_waitcnt lgkmcnt(0)
	s_barrier

.LBB0_213:
	s_mul_hi_i32 s4, s40, 0x66666667
	s_lshr_b32 s5, s4, 31
	s_ashr_i32 s4, s4, 3
	s_add_i32 s4, s4, s5
	s_lshl_b32 s5, s4, 3
	s_mul_i32 s4, s4, 20
	s_or_b32 s5, s5, s33
	s_sub_i32 s4, s40, s4
	s_lshl_b32 s41, s5, 7
	s_lshl_b32 s6, s4, 7
	s_mul_i32 s5, s5, 5
	s_mul_i32 s4, s4, 3
	s_add_i32 s4, s5, s4
	s_ashr_i32 s5, s4, 31
	s_lshr_b32 s5, s5, 30
	v_mov_b32_e32 v18, v138
	s_add_i32 s5, s4, s5
	s_and_b32 s5, s5, -4
	v_ashrrev_i32_e32 v0, 6, v18
	v_bfe_u32 v1, v18, 3, 3
	v_bitop3_b32 v8, v1, v18, 7 bitop3:0x78
	s_sub_i32 s7, s4, s5
	v_lshl_or_b32 v12, v0, 5, v1
	v_and_b32_e32 v20, 1, v0
	s_lshl_b32 s8, s7, 6
	v_lshlrev_b32_e32 v26, 12, v0
	v_add_u32_e32 v0, s41, v12
	v_lshlrev_b32_e32 v112, 3, v8
	v_or_b32_e32 v2, s8, v112
	v_ashrrev_i32_e32 v1, 31, v0
	v_lshlrev_b64 v[0:1], 9, v[0:1]
	v_ashrrev_i32_e32 v3, 31, v2
	v_lshl_add_u64 v[0:1], s[14:15], 0, v[0:1]
	v_lshlrev_b64 v[10:11], 1, v[2:3]
	v_readfirstlane_b32 s4, v26
	v_lshl_add_u64 v[2:3], v[0:1], 0, v[10:11]
	s_mov_b32 m0, s4
	v_or_b32_e32 v14, 8, v12
	global_load_lds_dwordx4 v[2:3], off
	v_add_u32_e32 v2, s41, v14
	v_ashrrev_i32_e32 v3, 31, v2
	v_lshlrev_b64 v[2:3], 9, v[2:3]
	v_or_b32_e32 v6, 0x400, v26
	v_lshl_add_u64 v[2:3], s[14:15], 0, v[2:3]
	v_readfirstlane_b32 s5, v6
	v_lshl_add_u64 v[4:5], v[2:3], 0, v[10:11]
	s_mov_b32 m0, s5
	v_or_b32_e32 v16, 16, v12
	global_load_lds_dwordx4 v[4:5], off
	v_add_u32_e32 v4, s41, v16
	v_ashrrev_i32_e32 v5, 31, v4
	v_lshlrev_b64 v[4:5], 9, v[4:5]
	v_or_b32_e32 v13, 0x800, v26
	v_lshl_add_u64 v[4:5], s[14:15], 0, v[4:5]
	v_readfirstlane_b32 s10, v13
	v_lshl_add_u64 v[6:7], v[4:5], 0, v[10:11]
	s_mov_b32 m0, s10
	v_or_b32_e32 v17, 24, v12
	global_load_lds_dwordx4 v[6:7], off
	v_add_u32_e32 v6, s41, v17
	v_ashrrev_i32_e32 v7, 31, v6
	v_lshlrev_b64 v[6:7], 9, v[6:7]
	v_or_b32_e32 v13, 0xc00, v26
	v_lshl_add_u64 v[6:7], s[14:15], 0, v[6:7]
	v_readfirstlane_b32 s28, v13
	v_lshl_add_u64 v[10:11], v[6:7], 0, v[10:11]
	s_mov_b32 m0, s28
	s_ashr_i32 s9, s8, 31
	global_load_lds_dwordx4 v[10:11], off
	v_add_u32_e32 v10, s6, v12
	v_ashrrev_i32_e32 v11, 31, v10
	v_lshlrev_b64 v[10:11], 9, v[10:11]
	v_add_u32_e32 v15, 0x4000, v26
	v_lshl_add_u64 v[10:11], s[26:27], 0, v[10:11]
	s_lshl_b64 s[8:9], s[8:9], 1
	v_lshl_add_u64 v[12:13], v[10:11], 0, s[8:9]
	v_lshlrev_b32_e32 v8, 4, v8
	v_readfirstlane_b32 s36, v15
	v_lshl_add_u64 v[12:13], v[12:13], 0, v[8:9]
	s_mov_b32 m0, s36
	v_add_u32_e32 v22, 0x4400, v26
	global_load_lds_dwordx4 v[12:13], off
	v_add_u32_e32 v12, s6, v14
	v_ashrrev_i32_e32 v13, 31, v12
	v_lshlrev_b64 v[12:13], 9, v[12:13]
	v_lshl_add_u64 v[12:13], s[26:27], 0, v[12:13]
	v_lshl_add_u64 v[14:15], v[12:13], 0, s[8:9]
	v_readfirstlane_b32 s37, v22
	v_lshl_add_u64 v[14:15], v[14:15], 0, v[8:9]
	s_mov_b32 m0, s37
	s_add_i32 s7, s7, 1
	global_load_lds_dwordx4 v[14:15], off
	v_add_u32_e32 v14, s6, v16
	v_ashrrev_i32_e32 v15, 31, v14
	v_lshlrev_b64 v[14:15], 9, v[14:15]
	v_lshl_add_u64 v[22:23], s[26:27], 0, v[14:15]
	v_add_u32_e32 v16, 0x4800, v26
	v_lshl_add_u64 v[14:15], v[22:23], 0, s[8:9]
	v_readfirstlane_b32 s52, v16
	v_lshl_add_u64 v[14:15], v[14:15], 0, v[8:9]
	s_mov_b32 m0, s52
	v_add_u32_e32 v16, 0x4c00, v26
	global_load_lds_dwordx4 v[14:15], off
	v_add_u32_e32 v14, s6, v17
	v_ashrrev_i32_e32 v15, 31, v14
	v_lshlrev_b64 v[14:15], 9, v[14:15]
	v_lshl_add_u64 v[24:25], s[26:27], 0, v[14:15]
	s_cmp_lg_u32 s7, 4
	v_lshl_add_u64 v[14:15], v[24:25], 0, s[8:9]
	v_readfirstlane_b32 s53, v16
	s_cselect_b32 s54, s7, 0
	v_lshl_add_u64 v[14:15], v[14:15], 0, v[8:9]
	s_mov_b32 m0, s53
	s_lshl_b32 s12, s54, 6
	global_load_lds_dwordx4 v[14:15], off
	v_lshl_add_u64 v[14:15], v[12:13], 0, v[8:9]
	v_lshl_add_u64 v[12:13], v[22:23], 0, v[8:9]
	v_or_b32_e32 v22, s12, v112
	v_add_u32_e32 v27, 0x8000, v26
	v_ashrrev_i32_e32 v23, 31, v22
	v_lshlrev_b64 v[22:23], 1, v[22:23]
	v_readfirstlane_b32 s7, v27
	v_add_u32_e32 v27, 0x8400, v26
	v_lshl_add_u64 v[16:17], v[10:11], 0, v[8:9]
	v_lshl_add_u64 v[10:11], v[24:25], 0, v[8:9]
	v_lshl_add_u64 v[24:25], v[0:1], 0, v[22:23]
	s_mov_b32 m0, s7
	v_readfirstlane_b32 s8, v27
	v_add_u32_e32 v27, 0x8800, v26
	s_waitcnt vmcnt(0) lgkmcnt(0)
	s_barrier
	global_load_lds_dwordx4 v[24:25], off
	v_lshl_add_u64 v[24:25], v[2:3], 0, v[22:23]
	s_mov_b32 m0, s8
	v_readfirstlane_b32 s9, v27
	global_load_lds_dwordx4 v[24:25], off
	v_lshl_add_u64 v[24:25], v[4:5], 0, v[22:23]
	s_mov_b32 m0, s9
	s_ashr_i32 s13, s12, 31
	global_load_lds_dwordx4 v[24:25], off
	v_add_u32_e32 v24, 0x8c00, v26
	v_lshl_add_u64 v[22:23], v[6:7], 0, v[22:23]
	v_readfirstlane_b32 s11, v24
	v_add_u32_e32 v24, 0xc000, v26
	s_mov_b32 m0, s11
	s_lshl_b64 s[50:51], s[12:13], 1
	v_readfirstlane_b32 s12, v24
	v_add_u32_e32 v24, 0xc400, v26
	global_load_lds_dwordx4 v[22:23], off
	v_lshl_add_u64 v[22:23], v[16:17], 0, s[50:51]
	s_mov_b32 m0, s12
	v_readfirstlane_b32 s13, v24
	v_add_u32_e32 v24, 0xc800, v26
	v_bfe_u32 v83, v18, 4, 2
	v_and_b32_e32 v21, 15, v18
	global_load_lds_dwordx4 v[22:23], off
	v_lshl_add_u64 v[22:23], v[14:15], 0, s[50:51]
	s_mov_b32 m0, s13
	v_readfirstlane_b32 s34, v24
	v_add_u32_e32 v24, 0xcc00, v26
	v_bitop3_b32 v8, v83, v18, 7 bitop3:0x78
	global_load_lds_dwordx4 v[22:23], off
	v_lshl_add_u64 v[22:23], v[12:13], 0, s[50:51]
	s_mov_b32 m0, s34
	v_readfirstlane_b32 s35, v24
	v_lshlrev_b32_e32 v26, 7, v21
	v_ashrrev_i32_e32 v19, 7, v18
	global_load_lds_dwordx4 v[22:23], off
	v_lshl_add_u64 v[22:23], v[10:11], 0, s[50:51]
	s_mov_b32 m0, s35
	v_lshlrev_b32_e32 v8, 4, v8
	v_lshl_or_b32 v92, v20, 13, v26
	global_load_lds_dwordx4 v[22:23], off
	s_setprio 1
	v_or_b32_e32 v113, v8, v92
	v_lshl_or_b32 v96, v19, 13, v26
	ds_read_b128 v[22:25], v113 offset:16384
	v_or_b32_e32 v114, v8, v96
	ds_read_b128 v[26:29], v113 offset:18432
	ds_read_b128 v[30:33], v114
	ds_read_b128 v[34:37], v114 offset:2048
	ds_read_b128 v[42:45], v113 offset:20480
	ds_read_b128 v[50:53], v113 offset:22528
	ds_read_b128 v[70:73], v114 offset:4096
	ds_read_b128 v[74:77], v114 offset:6144
	v_and_b32_e32 v8, 7, v18
	v_bitop3_b32 v8, v83, v8, 4 bitop3:0x36
	v_lshlrev_b32_e32 v8, 4, v8
	v_or_b32_e32 v83, v8, v92
	s_waitcnt lgkmcnt(0)
	v_mfma_f32_16x16x32_bf16 v[38:41], v[22:25], v[30:33], 0
	ds_read_b128 v[92:95], v83 offset:16384
	v_or_b32_e32 v115, v8, v96
	s_add_i32 s54, s54, 1
	v_mfma_f32_16x16x32_bf16 v[46:49], v[26:29], v[30:33], 0
	s_cmp_lg_u32 s54, 4
	s_cselect_b32 s54, s54, 0
	s_lshl_b32 s50, s54, 6
	v_mfma_f32_16x16x32_bf16 v[54:57], v[42:45], v[30:33], 0
	s_mov_b32 m0, s4
	s_ashr_i32 s51, s50, 31
	s_add_i32 s54, s54, 1
	v_mfma_f32_16x16x32_bf16 v[30:33], v[50:53], v[30:33], 0
	v_lshl_or_b32 v19, v19, 6, v21
	v_mfma_f32_16x16x32_bf16 v[58:61], v[22:25], v[34:37], 0
	v_mfma_f32_16x16x32_bf16 v[62:65], v[26:29], v[34:37], 0
	v_mfma_f32_16x16x32_bf16 v[66:69], v[42:45], v[34:37], 0
	v_mfma_f32_16x16x32_bf16 v[34:37], v[50:53], v[34:37], 0
	v_mfma_f32_16x16x32_bf16 v[78:81], v[22:25], v[70:73], 0
	v_mfma_f32_16x16x32_bf16 v[84:87], v[26:29], v[70:73], 0
	v_mfma_f32_16x16x32_bf16 v[88:91], v[42:45], v[70:73], 0
	v_mfma_f32_16x16x32_bf16 v[70:73], v[50:53], v[70:73], 0
	v_mfma_f32_16x16x32_bf16 v[22:25], v[22:25], v[74:77], 0
	v_mfma_f32_16x16x32_bf16 v[26:29], v[26:29], v[74:77], 0
	v_mfma_f32_16x16x32_bf16 v[42:45], v[42:45], v[74:77], 0
	v_mfma_f32_16x16x32_bf16 v[50:53], v[50:53], v[74:77], 0
	ds_read_b128 v[74:77], v83 offset:18432
	ds_read_b128 v[96:99], v115
	ds_read_b128 v[100:103], v115 offset:2048
	ds_read_b128 v[104:107], v83 offset:20480
	ds_read_b128 v[108:111], v83 offset:22528
	s_waitcnt lgkmcnt(3)
	v_mfma_f32_16x16x32_bf16 v[38:41], v[92:95], v[96:99], v[38:41]
	v_mfma_f32_16x16x32_bf16 v[46:49], v[74:77], v[96:99], v[46:49]
	s_waitcnt lgkmcnt(1)
	v_mfma_f32_16x16x32_bf16 v[54:57], v[104:107], v[96:99], v[54:57]
	s_waitcnt lgkmcnt(0)
	v_mfma_f32_16x16x32_bf16 v[30:33], v[108:111], v[96:99], v[30:33]
	v_mfma_f32_16x16x32_bf16 v[58:61], v[92:95], v[100:103], v[58:61]
	v_mfma_f32_16x16x32_bf16 v[62:65], v[74:77], v[100:103], v[62:65]
	v_mfma_f32_16x16x32_bf16 v[66:69], v[104:107], v[100:103], v[66:69]
	v_mfma_f32_16x16x32_bf16 v[34:37], v[108:111], v[100:103], v[34:37]
	ds_read_b128 v[96:99], v115 offset:4096
	ds_read_b128 v[100:103], v115 offset:6144
	s_setprio 0
	s_waitcnt vmcnt(0) lgkmcnt(0)
	s_barrier
	v_mfma_f32_16x16x32_bf16 v[84:87], v[74:77], v[96:99], v[84:87]
	v_mfma_f32_16x16x32_bf16 v[26:29], v[74:77], v[100:103], v[26:29]
	v_or_b32_e32 v74, s50, v112
	v_ashrrev_i32_e32 v75, 31, v74
	v_lshlrev_b64 v[74:75], 1, v[74:75]
	v_lshl_add_u64 v[76:77], v[0:1], 0, v[74:75]
	global_load_lds_dwordx4 v[76:77], off
	v_lshl_add_u64 v[76:77], v[2:3], 0, v[74:75]
	s_mov_b32 m0, s5
	s_lshl_b64 s[4:5], s[50:51], 1
	global_load_lds_dwordx4 v[76:77], off
	v_lshl_add_u64 v[76:77], v[4:5], 0, v[74:75]
	s_mov_b32 m0, s10
	v_lshl_add_u64 v[74:75], v[6:7], 0, v[74:75]
	global_load_lds_dwordx4 v[76:77], off
	s_mov_b32 m0, s28
	v_mfma_f32_16x16x32_bf16 v[78:81], v[92:95], v[96:99], v[78:81]
	global_load_lds_dwordx4 v[74:75], off
	v_lshl_add_u64 v[74:75], v[16:17], 0, s[4:5]
	s_mov_b32 m0, s36
	v_mfma_f32_16x16x32_bf16 v[88:91], v[104:107], v[96:99], v[88:91]
	global_load_lds_dwordx4 v[74:75], off
	v_lshl_add_u64 v[74:75], v[14:15], 0, s[4:5]
	s_mov_b32 m0, s37
	v_mfma_f32_16x16x32_bf16 v[70:73], v[108:111], v[96:99], v[70:73]
	global_load_lds_dwordx4 v[74:75], off
	v_lshl_add_u64 v[74:75], v[12:13], 0, s[4:5]
	s_mov_b32 m0, s52
	v_mfma_f32_16x16x32_bf16 v[22:25], v[92:95], v[100:103], v[22:25]
	global_load_lds_dwordx4 v[74:75], off
	v_lshl_add_u64 v[74:75], v[10:11], 0, s[4:5]
	s_mov_b32 m0, s53
	v_mfma_f32_16x16x32_bf16 v[42:45], v[104:107], v[100:103], v[42:45]
	global_load_lds_dwordx4 v[74:75], off
	s_setprio 1
	ds_read_b128 v[74:77], v113 offset:49152
	v_mfma_f32_16x16x32_bf16 v[50:53], v[108:111], v[100:103], v[50:53]
	ds_read_b128 v[92:95], v113 offset:51200
	ds_read_b128 v[96:99], v114 offset:32768
	ds_read_b128 v[100:103], v114 offset:34816
	ds_read_b128 v[104:107], v113 offset:53248
	ds_read_b128 v[108:111], v113 offset:55296
	s_waitcnt lgkmcnt(0)
	v_mfma_f32_16x16x32_bf16 v[38:41], v[74:77], v[96:99], v[38:41]
	s_lshl_b32 s4, s54, 6
	s_cmp_lg_u32 s54, 4
	s_cselect_b32 s4, s4, 0
	v_mfma_f32_16x16x32_bf16 v[46:49], v[92:95], v[96:99], v[46:49]
	v_or_b32_e32 v8, s4, v112
	v_lshlrev_b32_e32 v8, 1, v8
	v_lshl_add_u64 v[0:1], v[0:1], 0, v[8:9]
	v_mfma_f32_16x16x32_bf16 v[54:57], v[104:107], v[96:99], v[54:57]
	s_mov_b32 m0, s7
	s_lshl_b32 s28, s4, 1
	s_cmpk_gt_u32 s6, 0x7ff
	v_mfma_f32_16x16x32_bf16 v[30:33], v[108:111], v[96:99], v[30:33]
	v_mfma_f32_16x16x32_bf16 v[58:61], v[74:77], v[100:103], v[58:61]
	v_mfma_f32_16x16x32_bf16 v[62:65], v[92:95], v[100:103], v[62:65]
	v_mfma_f32_16x16x32_bf16 v[66:69], v[104:107], v[100:103], v[66:69]
	v_mfma_f32_16x16x32_bf16 v[34:37], v[108:111], v[100:103], v[34:37]
	ds_read_b128 v[96:99], v114 offset:36864
	ds_read_b128 v[100:103], v114 offset:38912
	s_waitcnt lgkmcnt(1)
	v_mfma_f32_16x16x32_bf16 v[78:81], v[74:77], v[96:99], v[78:81]
	v_mfma_f32_16x16x32_bf16 v[84:87], v[92:95], v[96:99], v[84:87]
	v_mfma_f32_16x16x32_bf16 v[88:91], v[104:107], v[96:99], v[88:91]
	v_mfma_f32_16x16x32_bf16 v[70:73], v[108:111], v[96:99], v[70:73]
	s_waitcnt lgkmcnt(0)
	v_mfma_f32_16x16x32_bf16 v[22:25], v[74:77], v[100:103], v[22:25]
	ds_read_b128 v[74:77], v83 offset:49152
	v_mfma_f32_16x16x32_bf16 v[26:29], v[92:95], v[100:103], v[26:29]
	v_mfma_f32_16x16x32_bf16 v[42:45], v[104:107], v[100:103], v[42:45]
	v_mfma_f32_16x16x32_bf16 v[50:53], v[108:111], v[100:103], v[50:53]
	ds_read_b128 v[92:95], v83 offset:51200
	ds_read_b128 v[96:99], v115 offset:32768
	ds_read_b128 v[100:103], v115 offset:34816
	ds_read_b128 v[104:107], v83 offset:53248
	ds_read_b128 v[108:111], v83 offset:55296
	s_waitcnt lgkmcnt(3)
	v_mfma_f32_16x16x32_bf16 v[38:41], v[74:77], v[96:99], v[38:41]
	v_mfma_f32_16x16x32_bf16 v[46:49], v[92:95], v[96:99], v[46:49]
	s_waitcnt lgkmcnt(1)
	v_mfma_f32_16x16x32_bf16 v[54:57], v[104:107], v[96:99], v[54:57]
	s_waitcnt lgkmcnt(0)
	v_mfma_f32_16x16x32_bf16 v[30:33], v[108:111], v[96:99], v[30:33]
	v_mfma_f32_16x16x32_bf16 v[58:61], v[74:77], v[100:103], v[58:61]
	v_mfma_f32_16x16x32_bf16 v[62:65], v[92:95], v[100:103], v[62:65]
	v_mfma_f32_16x16x32_bf16 v[66:69], v[104:107], v[100:103], v[66:69]
	v_mfma_f32_16x16x32_bf16 v[34:37], v[108:111], v[100:103], v[34:37]
	ds_read_b128 v[96:99], v115 offset:36864
	ds_read_b128 v[100:103], v115 offset:38912
	s_setprio 0
	s_waitcnt vmcnt(0) lgkmcnt(0)
	s_barrier
	global_load_lds_dwordx4 v[0:1], off
	v_lshl_add_u64 v[0:1], v[2:3], 0, v[8:9]
	s_mov_b32 m0, s8
	v_mfma_f32_16x16x32_bf16 v[78:81], v[74:77], v[96:99], v[78:81]
	global_load_lds_dwordx4 v[0:1], off
	v_lshl_add_u64 v[0:1], v[4:5], 0, v[8:9]
	s_mov_b32 m0, s9
	v_mfma_f32_16x16x32_bf16 v[84:87], v[92:95], v[96:99], v[84:87]
	global_load_lds_dwordx4 v[0:1], off
	v_lshl_add_u64 v[0:1], v[6:7], 0, v[8:9]
	s_mov_b32 m0, s11
	v_mfma_f32_16x16x32_bf16 v[22:25], v[74:77], v[100:103], v[22:25]
	global_load_lds_dwordx4 v[0:1], off
	v_lshl_add_u64 v[0:1], v[16:17], 0, s[28:29]
	s_mov_b32 m0, s12
	v_mfma_f32_16x16x32_bf16 v[26:29], v[92:95], v[100:103], v[26:29]
	global_load_lds_dwordx4 v[0:1], off
	v_lshl_add_u64 v[0:1], v[14:15], 0, s[28:29]
	s_mov_b32 m0, s13
	v_mfma_f32_16x16x32_bf16 v[4:7], v[108:111], v[100:103], v[50:53]
	global_load_lds_dwordx4 v[0:1], off
	v_lshl_add_u64 v[0:1], v[12:13], 0, s[28:29]
	s_mov_b32 m0, s34
	v_mfma_f32_16x16x32_bf16 v[88:91], v[104:107], v[96:99], v[88:91]
	global_load_lds_dwordx4 v[0:1], off
	v_lshl_add_u64 v[0:1], v[10:11], 0, s[28:29]
	s_mov_b32 m0, s35
	v_mfma_f32_16x16x32_bf16 v[70:73], v[108:111], v[96:99], v[70:73]
	global_load_lds_dwordx4 v[0:1], off
	s_setprio 1
	ds_read_b128 v[0:3], v113 offset:16384
	ds_read_b128 v[10:13], v113 offset:18432
	ds_read_b128 v[14:17], v114
	ds_read_b128 v[50:53], v114 offset:2048
	ds_read_b128 v[74:77], v113 offset:20480
	ds_read_b128 v[92:95], v113 offset:22528
	s_waitcnt lgkmcnt(0)
	v_mfma_f32_16x16x32_bf16 v[38:41], v[0:3], v[14:17], v[38:41]
	v_and_b32_e32 v8, 48, v18
	v_lshl_or_b32 v8, v20, 8, v8
	v_mad_u64_u32 v[20:21], s[4:5], v19, s31, v[8:9]
	v_mfma_f32_16x16x32_bf16 v[46:49], v[10:13], v[14:17], v[46:49]
	s_cselect_b64 s[34:35], -1, 0
	s_mov_b32 s28, 0
	v_mfma_f32_16x16x32_bf16 v[54:57], v[74:77], v[14:17], v[54:57]
	v_mfma_f32_16x16x32_bf16 v[14:17], v[92:95], v[14:17], v[30:33]
	v_mfma_f32_16x16x32_bf16 v[30:33], v[0:3], v[50:53], v[58:61]
	v_mfma_f32_16x16x32_bf16 v[58:61], v[10:13], v[50:53], v[62:65]
	v_mfma_f32_16x16x32_bf16 v[62:65], v[74:77], v[50:53], v[66:69]
	v_mfma_f32_16x16x32_bf16 v[34:37], v[92:95], v[50:53], v[34:37]
	ds_read_b128 v[50:53], v114 offset:4096
	s_nop 0
	ds_read_b128 v[66:69], v114 offset:6144
	v_mfma_f32_16x16x32_bf16 v[42:45], v[104:107], v[100:103], v[42:45]
	s_waitcnt lgkmcnt(1)
	v_mfma_f32_16x16x32_bf16 v[78:81], v[0:3], v[50:53], v[78:81]
	v_mfma_f32_16x16x32_bf16 v[84:87], v[10:13], v[50:53], v[84:87]
	v_mfma_f32_16x16x32_bf16 v[88:91], v[74:77], v[50:53], v[88:91]
	v_mfma_f32_16x16x32_bf16 v[50:53], v[92:95], v[50:53], v[70:73]
	s_waitcnt lgkmcnt(0)
	v_mfma_f32_16x16x32_bf16 v[0:3], v[0:3], v[66:69], v[22:25]
	v_mfma_f32_16x16x32_bf16 v[10:13], v[10:13], v[66:69], v[26:29]
	v_mfma_f32_16x16x32_bf16 v[22:25], v[74:77], v[66:69], v[42:45]
	s_nop 1
	ds_read_b128 v[26:29], v83 offset:16384
	v_mfma_f32_16x16x32_bf16 v[4:7], v[92:95], v[66:69], v[4:7]
	ds_read_b128 v[42:45], v83 offset:18432
	ds_read_b128 v[66:69], v115
	ds_read_b128 v[70:73], v115 offset:2048
	ds_read_b128 v[74:77], v83 offset:20480
	ds_read_b128 v[92:95], v83 offset:22528
	s_waitcnt lgkmcnt(3)
	v_mfma_f32_16x16x32_bf16 v[38:41], v[26:29], v[66:69], v[38:41]
	v_mfma_f32_16x16x32_bf16 v[46:49], v[42:45], v[66:69], v[46:49]
	s_waitcnt lgkmcnt(1)
	v_mfma_f32_16x16x32_bf16 v[54:57], v[74:77], v[66:69], v[54:57]
	s_waitcnt lgkmcnt(0)
	v_mfma_f32_16x16x32_bf16 v[14:17], v[92:95], v[66:69], v[14:17]
	v_mfma_f32_16x16x32_bf16 v[30:33], v[26:29], v[70:73], v[30:33]
	v_mfma_f32_16x16x32_bf16 v[58:61], v[42:45], v[70:73], v[58:61]
	v_mfma_f32_16x16x32_bf16 v[62:65], v[74:77], v[70:73], v[62:65]
	v_mfma_f32_16x16x32_bf16 v[34:37], v[92:95], v[70:73], v[34:37]
	ds_read_b128 v[66:69], v115 offset:4096
	ds_read_b128 v[70:73], v115 offset:6144
	s_setprio 0
	s_waitcnt vmcnt(0) lgkmcnt(0)
	s_barrier
	v_mfma_f32_16x16x32_bf16 v[78:81], v[26:29], v[66:69], v[78:81]
	v_mfma_f32_16x16x32_bf16 v[84:87], v[42:45], v[66:69], v[84:87]
	v_mfma_f32_16x16x32_bf16 v[88:91], v[74:77], v[66:69], v[88:91]
	v_mfma_f32_16x16x32_bf16 v[50:53], v[92:95], v[66:69], v[50:53]
	ds_read_b128 v[66:69], v113 offset:51200
	v_mfma_f32_16x16x32_bf16 v[0:3], v[26:29], v[70:73], v[0:3]
	ds_read_b128 v[26:29], v113 offset:49152
	v_mfma_f32_16x16x32_bf16 v[10:13], v[42:45], v[70:73], v[10:13]
	ds_read_b128 v[42:45], v114 offset:32768
	v_mfma_f32_16x16x32_bf16 v[22:25], v[74:77], v[70:73], v[22:25]
	ds_read_b128 v[74:77], v113 offset:55296
	v_mfma_f32_16x16x32_bf16 v[4:7], v[92:95], v[70:73], v[4:7]
	ds_read_b128 v[70:73], v113 offset:53248
	s_waitcnt lgkmcnt(2)
	v_mfma_f32_16x16x32_bf16 v[38:41], v[26:29], v[42:45], v[38:41]
	v_mfma_f32_16x16x32_bf16 v[46:49], v[66:69], v[42:45], v[46:49]
	s_waitcnt lgkmcnt(0)
	v_mfma_f32_16x16x32_bf16 v[54:57], v[70:73], v[42:45], v[54:57]
	v_mfma_f32_16x16x32_bf16 v[14:17], v[74:77], v[42:45], v[14:17]
	ds_read_b128 v[42:45], v114 offset:34816
	s_waitcnt lgkmcnt(0)
	v_mfma_f32_16x16x32_bf16 v[30:33], v[26:29], v[42:45], v[30:33]
	v_mfma_f32_16x16x32_bf16 v[58:61], v[66:69], v[42:45], v[58:61]
	v_mfma_f32_16x16x32_bf16 v[62:65], v[70:73], v[42:45], v[62:65]
	v_mfma_f32_16x16x32_bf16 v[34:37], v[74:77], v[42:45], v[34:37]
	ds_read_b128 v[42:45], v114 offset:36864
	s_waitcnt lgkmcnt(0)
	v_mfma_f32_16x16x32_bf16 v[78:81], v[26:29], v[42:45], v[78:81]
	v_mfma_f32_16x16x32_bf16 v[84:87], v[66:69], v[42:45], v[84:87]
	v_mfma_f32_16x16x32_bf16 v[88:91], v[70:73], v[42:45], v[88:91]
	v_mfma_f32_16x16x32_bf16 v[42:45], v[74:77], v[42:45], v[50:53]
	s_nop 2
	ds_read_b128 v[50:53], v114 offset:38912
	s_waitcnt lgkmcnt(0)
	v_mfma_f32_16x16x32_bf16 v[0:3], v[26:29], v[50:53], v[0:3]
	ds_read_b128 v[26:29], v83 offset:49152
	v_mfma_f32_16x16x32_bf16 v[10:13], v[66:69], v[50:53], v[10:13]
	ds_read_b128 v[66:69], v83 offset:51200
	v_mfma_f32_16x16x32_bf16 v[22:25], v[70:73], v[50:53], v[22:25]
	ds_read_b128 v[70:73], v83 offset:53248
	v_mfma_f32_16x16x32_bf16 v[4:7], v[74:77], v[50:53], v[4:7]
	ds_read_b128 v[74:77], v83 offset:55296
	ds_read_b128 v[50:53], v115 offset:32768
	s_waitcnt lgkmcnt(0)
	v_mfma_f32_16x16x32_bf16 v[38:41], v[26:29], v[50:53], v[38:41]
	v_mfma_f32_16x16x32_bf16 v[46:49], v[66:69], v[50:53], v[46:49]
	v_mfma_f32_16x16x32_bf16 v[54:57], v[70:73], v[50:53], v[54:57]
	v_mfma_f32_16x16x32_bf16 v[14:17], v[74:77], v[50:53], v[14:17]
	ds_read_b128 v[50:53], v115 offset:34816
	ds_read_b128 v[92:95], v115 offset:38912
	ds_read_b128 v[96:99], v115 offset:36864
	s_waitcnt lgkmcnt(0)
	v_mfma_f32_16x16x32_bf16 v[30:33], v[26:29], v[50:53], v[30:33]
	s_barrier
	v_mfma_f32_16x16x32_bf16 v[58:61], v[66:69], v[50:53], v[58:61]
	s_barrier
	ds_write_b128 v20, v[38:41]
	ds_write_b128 v20, v[46:49] offset:64
	ds_write_b128 v20, v[54:57] offset:128
	v_mfma_f32_16x16x32_bf16 v[62:65], v[70:73], v[50:53], v[62:65]
	ds_write_b128 v20, v[14:17] offset:192
	ds_write_b128 v20, v[30:33] offset:8448
	s_nop 0
	ds_write_b128 v20, v[58:61] offset:8512
	v_mfma_f32_16x16x32_bf16 v[34:37], v[74:77], v[50:53], v[34:37]
	v_mfma_f32_16x16x32_bf16 v[50:53], v[26:29], v[96:99], v[78:81]
	s_nop 1
	ds_write_b128 v20, v[62:65] offset:8576
	s_nop 3
	ds_write_b128 v20, v[34:37] offset:8640
	ds_write_b128 v20, v[50:53] offset:16896
	v_mfma_f32_16x16x32_bf16 v[78:81], v[66:69], v[96:99], v[84:87]
	v_mfma_f32_16x16x32_bf16 v[0:3], v[26:29], v[92:95], v[0:3]
	v_mfma_f32_16x16x32_bf16 v[84:87], v[70:73], v[96:99], v[88:91]
	v_mfma_f32_16x16x32_bf16 v[10:13], v[66:69], v[92:95], v[10:13]
	v_mfma_f32_16x16x32_bf16 v[38:41], v[74:77], v[96:99], v[42:45]
	s_nop 3
	ds_write_b128 v20, v[78:81] offset:16960
	s_nop 0
	ds_write_b128 v20, v[84:87] offset:17024
	s_nop 0
	ds_write_b128 v20, v[38:41] offset:17088
	v_mfma_f32_16x16x32_bf16 v[14:17], v[70:73], v[92:95], v[22:25]
	ds_write_b128 v20, v[0:3] offset:25344
	ds_write_b128 v20, v[10:13] offset:25408
	s_nop 5
	ds_write_b128 v20, v[14:17] offset:25472
	v_mfma_f32_16x16x32_bf16 v[0:3], v[74:77], v[92:95], v[4:7]
	s_nop 7
	ds_write_b128 v20, v[0:3] offset:25536
	v_lshlrev_b32_e32 v0, 3, v18
	v_and_b32_e32 v1, 0x78, v0
	v_or_b32_e32 v0, s6, v1
	v_lshlrev_b32_e32 v10, 2, v1
	v_ashrrev_i32_e32 v1, 31, v0
	v_mov_b32_e32 v8, v0
	v_cmp_lt_i32_e64 s[4:5], s38, v0
	v_lshl_add_u64 v[12:13], v[0:1], 1, s[80:81]
	v_lshl_add_u64 v[14:15], v[8:9], 2, s[66:67]
	v_lshl_add_u64 v[16:17], v[0:1], 2, s[62:63]
	s_waitcnt lgkmcnt(0)
	s_barrier
	s_branch .LBB0_215

.LBB0_301:
	s_add_i32 s5, s28, 1
	s_cmp_lg_u32 s5, 16
	s_cselect_b32 s28, s5, 0
	s_add_i32 s5, s4, 0x8000
	s_lshl_b32 s30, s28, 6
	s_and_b32 s13, s5, 0x8000
	v_or_b32_e32 v100, s30, v91
	v_add_u32_e32 v102, s13, v92
	v_ashrrev_i32_e32 v101, 31, v100
	v_readfirstlane_b32 s13, v102
	v_add_u32_e32 v104, 0x400, v102
	v_add_u32_e32 v105, 0x800, v102
	v_add_u32_e32 v106, 0xc00, v102
	v_add_u32_e32 v107, 0x4000, v102
	v_add_u32_e32 v108, 0x4400, v102
	v_add_u32_e32 v110, 0x4800, v102
	v_add_u32_e32 v112, 0x4c00, v102
	v_lshlrev_b64 v[102:103], 1, v[100:101]
	v_mov_b32_e32 v101, v65
	s_ashr_i32 s31, s30, 31
	v_lshlrev_b64 v[114:115], 1, v[100:101]
	s_lshl_b64 s[30:31], s[30:31], 1
	v_lshl_add_u64 v[120:121], v[66:67], 0, v[114:115]
	v_readfirstlane_b32 s29, v104
	v_readfirstlane_b32 s34, v105
	v_readfirstlane_b32 s35, v106
	v_lshl_add_u64 v[104:105], v[82:83], 0, s[30:31]
	v_readfirstlane_b32 s36, v107
	v_lshl_add_u64 v[106:107], v[84:85], 0, s[30:31]
	v_readfirstlane_b32 s37, v108
	v_lshl_add_u64 v[108:109], v[86:87], 0, s[30:31]
	v_readfirstlane_b32 s38, v110
	v_lshl_add_u64 v[110:111], v[88:89], 0, s[30:31]
	v_readfirstlane_b32 s30, v112
	v_lshl_add_u64 v[112:113], v[68:69], 0, v[102:103]
	v_lshl_add_u64 v[122:123], v[70:71], 0, v[114:115]
	v_lshl_add_u64 v[120:121], v[120:121], 0, s[10:11]
	v_cmp_gt_i32_e32 vcc, s24, v100
	v_lshl_add_u64 v[116:117], v[72:73], 0, v[102:103]
	v_lshl_add_u64 v[124:125], v[74:75], 0, v[114:115]
	v_lshl_add_u64 v[122:123], v[122:123], 0, s[10:11]
	v_cndmask_b32_e32 v101, v121, v113, vcc
	v_cndmask_b32_e32 v100, v120, v112, vcc
	s_mov_b32 m0, s13
	s_waitcnt vmcnt(0) lgkmcnt(0)
	s_barrier
	v_lshl_add_u64 v[118:119], v[76:77], 0, v[102:103]
	v_lshl_add_u64 v[114:115], v[78:79], 0, v[114:115]
	v_lshl_add_u64 v[124:125], v[124:125], 0, s[10:11]
	v_cndmask_b32_e32 v113, v123, v117, vcc
	v_cndmask_b32_e32 v112, v122, v116, vcc
	global_load_lds_dwordx4 v[100:101], off
	s_mov_b32 m0, s29
	v_lshl_add_u64 v[102:103], v[80:81], 0, v[102:103]
	v_lshl_add_u64 v[114:115], v[114:115], 0, s[10:11]
	v_cndmask_b32_e32 v117, v125, v119, vcc
	v_cndmask_b32_e32 v116, v124, v118, vcc
	global_load_lds_dwordx4 v[112:113], off
	s_mov_b32 m0, s34
	v_cndmask_b32_e32 v103, v115, v103, vcc
	v_cndmask_b32_e32 v102, v114, v102, vcc
	global_load_lds_dwordx4 v[116:117], off
	s_mov_b32 m0, s35
	s_and_b32 s4, s4, 0x8000
	global_load_lds_dwordx4 v[102:103], off
	s_mov_b32 m0, s36
	v_lshl_or_b32 v99, v98, 1, s4
	global_load_lds_dwordx4 v[104:105], off
	s_mov_b32 m0, s37
	v_add_u32_e32 v126, v99, v64
	global_load_lds_dwordx4 v[106:107], off
	s_mov_b32 m0, s38
	v_add_u32_e32 v99, v99, v97
	global_load_lds_dwordx4 v[108:109], off
	s_mov_b32 m0, s30
	s_cmp_eq_u32 s5, 0x78000
	global_load_lds_dwordx4 v[110:111], off
	s_setprio 1
	ds_read_b128 v[100:103], v99 offset:16384
	ds_read_b128 v[104:107], v99 offset:18432
	ds_read_b128 v[108:111], v126
	ds_read_b128 v[112:115], v126 offset:2048
	ds_read_b128 v[116:119], v99 offset:20480
	ds_read_b128 v[120:123], v99 offset:22528
	s_waitcnt lgkmcnt(0)
	v_mfma_f32_16x16x32_bf16 v[60:63], v[100:103], v[108:111], v[60:63]
	v_lshl_or_b32 v99, v96, 1, s4
	v_add_u32_e32 v124, v99, v64
	v_add_u32_e32 v99, v99, v97
	v_mfma_f32_16x16x32_bf16 v[56:59], v[104:107], v[108:111], v[56:59]
	s_mov_b32 s4, s5
	v_mfma_f32_16x16x32_bf16 v[48:51], v[116:119], v[108:111], v[48:51]
	v_mfma_f32_16x16x32_bf16 v[32:35], v[120:123], v[108:111], v[32:35]
	v_mfma_f32_16x16x32_bf16 v[28:31], v[100:103], v[112:115], v[28:31]
	v_mfma_f32_16x16x32_bf16 v[24:27], v[104:107], v[112:115], v[24:27]
	v_mfma_f32_16x16x32_bf16 v[20:23], v[116:119], v[112:115], v[20:23]
	v_mfma_f32_16x16x32_bf16 v[16:19], v[120:123], v[112:115], v[16:19]
	ds_read_b128 v[108:111], v126 offset:4096
	ds_read_b128 v[112:115], v126 offset:6144
	s_waitcnt lgkmcnt(1)
	v_mfma_f32_16x16x32_bf16 v[12:15], v[100:103], v[108:111], v[12:15]
	v_mfma_f32_16x16x32_bf16 v[8:11], v[104:107], v[108:111], v[8:11]
	v_mfma_f32_16x16x32_bf16 v[4:7], v[116:119], v[108:111], v[4:7]
	v_mfma_f32_16x16x32_bf16 v[0:3], v[120:123], v[108:111], v[0:3]
	s_waitcnt lgkmcnt(0)
	v_mfma_f32_16x16x32_bf16 v[44:47], v[100:103], v[112:115], v[44:47]
	v_mfma_f32_16x16x32_bf16 v[52:55], v[104:107], v[112:115], v[52:55]
	ds_read_b128 v[100:103], v99 offset:16384
	ds_read_b128 v[104:107], v99 offset:18432
	v_mfma_f32_16x16x32_bf16 v[40:43], v[116:119], v[112:115], v[40:43]
	v_mfma_f32_16x16x32_bf16 v[36:39], v[120:123], v[112:115], v[36:39]
	ds_read_b128 v[108:111], v124
	ds_read_b128 v[112:115], v124 offset:2048
	ds_read_b128 v[116:119], v99 offset:20480
	ds_read_b128 v[120:123], v99 offset:22528
	s_waitcnt lgkmcnt(3)
	v_mfma_f32_16x16x32_bf16 v[60:63], v[100:103], v[108:111], v[60:63]
	v_mfma_f32_16x16x32_bf16 v[56:59], v[104:107], v[108:111], v[56:59]
	s_waitcnt lgkmcnt(1)
	v_mfma_f32_16x16x32_bf16 v[48:51], v[116:119], v[108:111], v[48:51]
	s_waitcnt lgkmcnt(0)
	v_mfma_f32_16x16x32_bf16 v[32:35], v[120:123], v[108:111], v[32:35]
	v_mfma_f32_16x16x32_bf16 v[28:31], v[100:103], v[112:115], v[28:31]
	v_mfma_f32_16x16x32_bf16 v[24:27], v[104:107], v[112:115], v[24:27]
	v_mfma_f32_16x16x32_bf16 v[20:23], v[116:119], v[112:115], v[20:23]
	v_mfma_f32_16x16x32_bf16 v[16:19], v[120:123], v[112:115], v[16:19]
	ds_read_b128 v[108:111], v124 offset:4096
	ds_read_b128 v[112:115], v124 offset:6144
	s_waitcnt lgkmcnt(1)
	v_mfma_f32_16x16x32_bf16 v[12:15], v[100:103], v[108:111], v[12:15]
	v_mfma_f32_16x16x32_bf16 v[8:11], v[104:107], v[108:111], v[8:11]
	v_mfma_f32_16x16x32_bf16 v[4:7], v[116:119], v[108:111], v[4:7]
	v_mfma_f32_16x16x32_bf16 v[0:3], v[120:123], v[108:111], v[0:3]
	s_waitcnt lgkmcnt(0)
	v_mfma_f32_16x16x32_bf16 v[44:47], v[100:103], v[112:115], v[44:47]
	v_mfma_f32_16x16x32_bf16 v[52:55], v[104:107], v[112:115], v[52:55]
	v_mfma_f32_16x16x32_bf16 v[40:43], v[116:119], v[112:115], v[40:43]
	v_mfma_f32_16x16x32_bf16 v[36:39], v[120:123], v[112:115], v[36:39]
	s_setprio 0
	s_cbranch_scc0 .LBB0_301
	v_lshlrev_b32_e32 v70, 1, v98
	v_add_u32_e32 v82, v70, v97
	v_add_u32_e32 v86, v70, v64
	s_waitcnt vmcnt(0)
	s_barrier
	ds_read_b128 v[66:69], v82 offset:49152
	ds_read_b128 v[74:77], v82 offset:51200
	ds_read_b128 v[70:73], v86 offset:32768
	ds_read_b128 v[78:81], v82 offset:53248
	ds_read_b128 v[82:85], v82 offset:55296
	s_waitcnt lgkmcnt(2)
	v_mfma_f32_16x16x32_bf16 v[60:63], v[66:69], v[70:73], v[60:63]
	v_mfma_f32_16x16x32_bf16 v[56:59], v[74:77], v[70:73], v[56:59]
	s_waitcnt lgkmcnt(1)
	v_mfma_f32_16x16x32_bf16 v[48:51], v[78:81], v[70:73], v[48:51]
	s_waitcnt lgkmcnt(0)
	v_mfma_f32_16x16x32_bf16 v[32:35], v[82:85], v[70:73], v[32:35]
	ds_read_b128 v[70:73], v86 offset:34816
	s_waitcnt lgkmcnt(0)
	v_mfma_f32_16x16x32_bf16 v[28:31], v[66:69], v[70:73], v[28:31]
	v_mfma_f32_16x16x32_bf16 v[24:27], v[74:77], v[70:73], v[24:27]
	v_mfma_f32_16x16x32_bf16 v[20:23], v[78:81], v[70:73], v[20:23]
	v_mfma_f32_16x16x32_bf16 v[16:19], v[82:85], v[70:73], v[16:19]
	ds_read_b128 v[70:73], v86 offset:36864
	s_waitcnt lgkmcnt(0)
	v_mfma_f32_16x16x32_bf16 v[12:15], v[66:69], v[70:73], v[12:15]
	v_mfma_f32_16x16x32_bf16 v[8:11], v[74:77], v[70:73], v[8:11]
	v_mfma_f32_16x16x32_bf16 v[4:7], v[78:81], v[70:73], v[4:7]
	v_mfma_f32_16x16x32_bf16 v[0:3], v[82:85], v[70:73], v[0:3]
	ds_read_b128 v[70:73], v86 offset:38912
	s_waitcnt lgkmcnt(0)
	v_mfma_f32_16x16x32_bf16 v[52:55], v[74:77], v[70:73], v[52:55]
	v_lshlrev_b32_e32 v74, 1, v96
	v_add_u32_e32 v86, v74, v97
	v_add_u32_e32 v64, v74, v64
	v_mfma_f32_16x16x32_bf16 v[44:47], v[66:69], v[70:73], v[44:47]
	ds_read_b128 v[66:69], v86 offset:49152
	ds_read_b128 v[74:77], v86 offset:51200
	v_mfma_f32_16x16x32_bf16 v[40:43], v[78:81], v[70:73], v[40:43]
	ds_read_b128 v[78:81], v86 offset:53248
	v_mfma_f32_16x16x32_bf16 v[36:39], v[82:85], v[70:73], v[36:39]
	ds_read_b128 v[82:85], v86 offset:55296
	ds_read_b128 v[70:73], v64 offset:32768
	s_waitcnt lgkmcnt(0)
	v_mfma_f32_16x16x32_bf16 v[60:63], v[66:69], v[70:73], v[60:63]
	v_mfma_f32_16x16x32_bf16 v[56:59], v[74:77], v[70:73], v[56:59]
	v_mfma_f32_16x16x32_bf16 v[48:51], v[78:81], v[70:73], v[48:51]
	v_mfma_f32_16x16x32_bf16 v[32:35], v[82:85], v[70:73], v[32:35]
	ds_read_b128 v[70:73], v64 offset:34816
	ds_read_b128 v[86:89], v64 offset:38912
	ds_read_b128 v[96:99], v64 offset:36864
	v_and_b32_e32 v64, 48, v90
	s_waitcnt lgkmcnt(2)
	v_mfma_f32_16x16x32_bf16 v[28:31], v[66:69], v[70:73], v[28:31]
	v_lshl_or_b32 v64, v93, 8, v64
	s_waitcnt lgkmcnt(0)
	s_barrier
	v_mfma_f32_16x16x32_bf16 v[20:23], v[78:81], v[70:73], v[20:23]
	s_barrier
	v_mfma_f32_16x16x32_bf16 v[24:27], v[74:77], v[70:73], v[24:27]
	v_mfma_f32_16x16x32_bf16 v[16:19], v[82:85], v[70:73], v[16:19]
	v_lshl_or_b32 v70, v94, 6, v95
	v_mad_u64_u32 v[70:71], s[4:5], v70, s25, v[64:65]
	v_mfma_f32_16x16x32_bf16 v[8:11], v[74:77], v[96:99], v[8:11]
	ds_write_b128 v70, v[60:63]
	ds_write_b128 v70, v[56:59] offset:64
	ds_write_b128 v70, v[48:51] offset:128
	ds_write_b128 v70, v[32:35] offset:192
	ds_write_b128 v70, v[28:31] offset:8448
	ds_write_b128 v70, v[24:27] offset:8512
	v_mfma_f32_16x16x32_bf16 v[12:15], v[66:69], v[96:99], v[12:15]
	ds_write_b128 v70, v[20:23] offset:8576
	ds_write_b128 v70, v[16:19] offset:8640
	s_nop 5
	ds_write_b128 v70, v[12:15] offset:16896
	v_mfma_f32_16x16x32_bf16 v[4:7], v[78:81], v[96:99], v[4:7]
	v_mfma_f32_16x16x32_bf16 v[0:3], v[82:85], v[96:99], v[0:3]
	ds_write_b128 v70, v[8:11] offset:16960
	s_nop 5
	ds_write_b128 v70, v[4:7] offset:17024
	ds_write_b128 v70, v[0:3] offset:17088
	v_and_b32_e32 v4, 64, v139
	v_mfma_f32_16x16x32_bf16 v[24:27], v[66:69], v[86:89], v[44:47]
	v_add_u32_e32 v4, 64, v4
	v_xor_b32_e32 v5, 2, v139
	v_mfma_f32_16x16x32_bf16 v[12:15], v[74:77], v[86:89], v[52:55]
	v_mfma_f32_16x16x32_bf16 v[0:3], v[78:81], v[86:89], v[40:43]
	s_nop 3
	ds_write_b128 v70, v[24:27] offset:25344
	s_nop 1
	ds_write_b128 v70, v[12:15] offset:25408
	ds_write_b128 v70, v[0:3] offset:25472
	v_mfma_f32_16x16x32_bf16 v[0:3], v[82:85], v[86:89], v[36:39]
	s_nop 7
	ds_write_b128 v70, v[0:3] offset:25536
	v_xor_b32_e32 v3, 1, v139
	v_cmp_lt_i32_e32 vcc, v3, v4
	v_lshl_or_b32 v0, v95, 3, s12
	v_ashrrev_i32_e32 v1, 31, v0
	v_cndmask_b32_e32 v3, v139, v3, vcc
	v_cmp_lt_i32_e32 vcc, v5, v4
	v_lshlrev_b32_e32 v2, 5, v95
	s_mov_b32 s12, 0
	v_cndmask_b32_e32 v5, v139, v5, vcc
	v_lshlrev_b32_e32 v10, 2, v5
	v_xor_b32_e32 v5, 4, v139
	v_cmp_lt_i32_e32 vcc, v5, v4
	v_lshlrev_b32_e32 v3, 2, v3
	v_lshl_add_u64 v[6:7], v[0:1], 1, s[58:59]
	v_cndmask_b32_e32 v5, v139, v5, vcc
	v_lshlrev_b32_e32 v11, 2, v5
	v_xor_b32_e32 v5, 8, v139
	v_cmp_lt_i32_e32 vcc, v5, v4
	s_waitcnt lgkmcnt(0)
	s_barrier
	v_cndmask_b32_e32 v4, v139, v5, vcc
	v_lshlrev_b32_e32 v12, 2, v4
	v_cmp_eq_u32_e32 vcc, 0, v95
	v_lshl_add_u64 v[4:5], v[0:1], 2, s[78:79]
	s_branch .LBB0_304

.LBB0_319:
	s_add_i32 s4, s4, 1
	s_cmp_lg_u32 s4, 16
	s_cselect_b32 s4, s4, 0
	s_add_i32 s6, s5, 0x8000
	s_lshl_b32 s8, s4, 6
	s_and_b32 s7, s6, 0x8000
	v_or_b32_e32 v94, s8, v89
	v_add_u32_e32 v96, s7, v88
	s_ashr_i32 s9, s8, 31
	v_ashrrev_i32_e32 v95, 31, v94
	v_readfirstlane_b32 s7, v96
	v_add_u32_e32 v97, 0x400, v96
	v_add_u32_e32 v98, 0x800, v96
	v_add_u32_e32 v99, 0xc00, v96
	v_add_u32_e32 v100, 0x4000, v96
	s_lshl_b64 s[8:9], s[8:9], 1
	v_add_u32_e32 v101, 0x4400, v96
	v_add_u32_e32 v102, 0x4800, v96
	v_add_u32_e32 v104, 0x4c00, v96
	v_lshlrev_b64 v[94:95], 1, v[94:95]
	v_readfirstlane_b32 s16, v97
	v_readfirstlane_b32 s17, v98
	v_readfirstlane_b32 s18, v99
	v_lshl_add_u64 v[96:97], v[74:75], 0, s[8:9]
	v_readfirstlane_b32 s19, v100
	v_lshl_add_u64 v[98:99], v[76:77], 0, s[8:9]
	v_readfirstlane_b32 s22, v101
	v_lshl_add_u64 v[100:101], v[78:79], 0, s[8:9]
	v_readfirstlane_b32 s23, v102
	v_lshl_add_u64 v[102:103], v[80:81], 0, s[8:9]
	v_readfirstlane_b32 s8, v104
	v_lshl_add_u64 v[104:105], v[66:67], 0, v[94:95]
	s_mov_b32 m0, s7
	s_waitcnt vmcnt(0) lgkmcnt(0)
	s_barrier
	v_lshl_add_u64 v[106:107], v[68:69], 0, v[94:95]
	global_load_lds_dwordx4 v[104:105], off
	s_mov_b32 m0, s16
	v_lshl_add_u64 v[108:109], v[70:71], 0, v[94:95]
	global_load_lds_dwordx4 v[106:107], off
	s_mov_b32 m0, s17
	v_lshl_add_u64 v[94:95], v[72:73], 0, v[94:95]
	global_load_lds_dwordx4 v[108:109], off
	s_mov_b32 m0, s18
	s_and_b32 s5, s5, 0x8000
	global_load_lds_dwordx4 v[94:95], off
	s_mov_b32 m0, s19
	v_lshl_or_b32 v93, v92, 1, s5
	global_load_lds_dwordx4 v[96:97], off
	s_mov_b32 m0, s22
	v_add_u32_e32 v118, v93, v64
	global_load_lds_dwordx4 v[98:99], off
	s_mov_b32 m0, s23
	v_add_u32_e32 v93, v93, v91
	global_load_lds_dwordx4 v[100:101], off
	s_mov_b32 m0, s8
	s_cmp_eq_u32 s6, 0x78000
	global_load_lds_dwordx4 v[102:103], off
	s_setprio 1
	ds_read_b128 v[94:97], v93 offset:16384
	ds_read_b128 v[98:101], v93 offset:18432
	ds_read_b128 v[102:105], v118
	ds_read_b128 v[106:109], v118 offset:2048
	ds_read_b128 v[110:113], v93 offset:20480
	ds_read_b128 v[114:117], v93 offset:22528
	s_waitcnt lgkmcnt(0)
	v_mfma_f32_16x16x32_bf16 v[60:63], v[94:97], v[102:105], v[60:63]
	v_lshl_or_b32 v93, v90, 1, s5
	s_mov_b32 s5, s6
	v_mfma_f32_16x16x32_bf16 v[56:59], v[98:101], v[102:105], v[56:59]
	v_mfma_f32_16x16x32_bf16 v[52:55], v[110:113], v[102:105], v[52:55]
	v_mfma_f32_16x16x32_bf16 v[40:43], v[114:117], v[102:105], v[40:43]
	v_mfma_f32_16x16x32_bf16 v[32:35], v[94:97], v[106:109], v[32:35]
	v_mfma_f32_16x16x32_bf16 v[28:31], v[98:101], v[106:109], v[28:31]
	v_mfma_f32_16x16x32_bf16 v[24:27], v[110:113], v[106:109], v[24:27]
	v_mfma_f32_16x16x32_bf16 v[20:23], v[114:117], v[106:109], v[20:23]
	ds_read_b128 v[102:105], v118 offset:4096
	ds_read_b128 v[106:109], v118 offset:6144
	v_add_u32_e32 v118, v93, v64
	v_add_u32_e32 v93, v93, v91
	s_waitcnt lgkmcnt(1)
	v_mfma_f32_16x16x32_bf16 v[12:15], v[94:97], v[102:105], v[12:15]
	v_mfma_f32_16x16x32_bf16 v[8:11], v[98:101], v[102:105], v[8:11]
	v_mfma_f32_16x16x32_bf16 v[4:7], v[110:113], v[102:105], v[4:7]
	v_mfma_f32_16x16x32_bf16 v[0:3], v[114:117], v[102:105], v[0:3]
	s_waitcnt lgkmcnt(0)
	v_mfma_f32_16x16x32_bf16 v[44:47], v[94:97], v[106:109], v[44:47]
	v_mfma_f32_16x16x32_bf16 v[48:51], v[98:101], v[106:109], v[48:51]
	ds_read_b128 v[94:97], v93 offset:16384
	ds_read_b128 v[98:101], v93 offset:18432
	v_mfma_f32_16x16x32_bf16 v[36:39], v[110:113], v[106:109], v[36:39]
	v_mfma_f32_16x16x32_bf16 v[16:19], v[114:117], v[106:109], v[16:19]
	ds_read_b128 v[102:105], v118
	ds_read_b128 v[106:109], v118 offset:2048
	ds_read_b128 v[110:113], v93 offset:20480
	ds_read_b128 v[114:117], v93 offset:22528
	s_waitcnt lgkmcnt(3)
	v_mfma_f32_16x16x32_bf16 v[60:63], v[94:97], v[102:105], v[60:63]
	v_mfma_f32_16x16x32_bf16 v[56:59], v[98:101], v[102:105], v[56:59]
	s_waitcnt lgkmcnt(1)
	v_mfma_f32_16x16x32_bf16 v[52:55], v[110:113], v[102:105], v[52:55]
	s_waitcnt lgkmcnt(0)
	v_mfma_f32_16x16x32_bf16 v[40:43], v[114:117], v[102:105], v[40:43]
	v_mfma_f32_16x16x32_bf16 v[32:35], v[94:97], v[106:109], v[32:35]
	v_mfma_f32_16x16x32_bf16 v[28:31], v[98:101], v[106:109], v[28:31]
	v_mfma_f32_16x16x32_bf16 v[24:27], v[110:113], v[106:109], v[24:27]
	v_mfma_f32_16x16x32_bf16 v[20:23], v[114:117], v[106:109], v[20:23]
	ds_read_b128 v[102:105], v118 offset:4096
	ds_read_b128 v[106:109], v118 offset:6144
	s_waitcnt lgkmcnt(1)
	v_mfma_f32_16x16x32_bf16 v[12:15], v[94:97], v[102:105], v[12:15]
	v_mfma_f32_16x16x32_bf16 v[8:11], v[98:101], v[102:105], v[8:11]
	v_mfma_f32_16x16x32_bf16 v[4:7], v[110:113], v[102:105], v[4:7]
	v_mfma_f32_16x16x32_bf16 v[0:3], v[114:117], v[102:105], v[0:3]
	s_waitcnt lgkmcnt(0)
	v_mfma_f32_16x16x32_bf16 v[44:47], v[94:97], v[106:109], v[44:47]
	v_mfma_f32_16x16x32_bf16 v[48:51], v[98:101], v[106:109], v[48:51]
	v_mfma_f32_16x16x32_bf16 v[36:39], v[110:113], v[106:109], v[36:39]
	v_mfma_f32_16x16x32_bf16 v[16:19], v[114:117], v[106:109], v[16:19]
	s_setprio 0
	s_cbranch_scc0 .LBB0_319
	v_lshlrev_b32_e32 v70, 1, v92
	v_add_u32_e32 v88, v70, v91
	s_waitcnt vmcnt(0)
	s_barrier
	ds_read_b128 v[66:69], v88 offset:49152
	ds_read_b128 v[74:77], v88 offset:51200
	ds_read_b128 v[78:81], v88 offset:53248
	ds_read_b128 v[92:95], v88 offset:55296
	v_add_u32_e32 v89, v70, v64
	ds_read_b128 v[70:73], v89 offset:32768
	s_waitcnt lgkmcnt(0)
	v_mfma_f32_16x16x32_bf16 v[60:63], v[66:69], v[70:73], v[60:63]
	v_lshlrev_b32_e32 v88, 1, v90
	v_add_u32_e32 v104, v88, v91
	v_add_u32_e32 v64, v88, v64
	v_mfma_f32_16x16x32_bf16 v[56:59], v[74:77], v[70:73], v[56:59]
	v_mfma_f32_16x16x32_bf16 v[52:55], v[78:81], v[70:73], v[52:55]
	v_mfma_f32_16x16x32_bf16 v[40:43], v[92:95], v[70:73], v[40:43]
	ds_read_b128 v[70:73], v89 offset:34816
	s_waitcnt lgkmcnt(0)
	v_mfma_f32_16x16x32_bf16 v[32:35], v[66:69], v[70:73], v[32:35]
	v_mfma_f32_16x16x32_bf16 v[28:31], v[74:77], v[70:73], v[28:31]
	v_mfma_f32_16x16x32_bf16 v[24:27], v[78:81], v[70:73], v[24:27]
	v_mfma_f32_16x16x32_bf16 v[20:23], v[92:95], v[70:73], v[20:23]
	ds_read_b128 v[70:73], v89 offset:36864
	s_waitcnt lgkmcnt(0)
	v_mfma_f32_16x16x32_bf16 v[12:15], v[66:69], v[70:73], v[12:15]
	v_mfma_f32_16x16x32_bf16 v[8:11], v[74:77], v[70:73], v[8:11]
	v_mfma_f32_16x16x32_bf16 v[4:7], v[78:81], v[70:73], v[4:7]
	v_mfma_f32_16x16x32_bf16 v[0:3], v[92:95], v[70:73], v[0:3]
	ds_read_b128 v[70:73], v89 offset:38912
	s_waitcnt lgkmcnt(0)
	v_mfma_f32_16x16x32_bf16 v[44:47], v[66:69], v[70:73], v[44:47]
	ds_read_b128 v[66:69], v104 offset:55296
	ds_read_b128 v[88:91], v104 offset:53248
	v_mfma_f32_16x16x32_bf16 v[48:51], v[74:77], v[70:73], v[48:51]
	ds_read_b128 v[74:77], v64 offset:38912
	ds_read_b128 v[96:99], v64 offset:36864
	ds_read_b128 v[100:103], v104 offset:51200
	ds_read_b128 v[104:107], v104 offset:49152
	v_mfma_f32_16x16x32_bf16 v[36:39], v[78:81], v[70:73], v[36:39]
	ds_read_b128 v[78:81], v64 offset:34816
	ds_read_b128 v[108:111], v64 offset:32768
	v_lshlrev_b32_e32 v64, 6, v87
	s_waitcnt lgkmcnt(0)
	v_mfma_f32_16x16x32_bf16 v[16:19], v[92:95], v[70:73], v[16:19]
	v_add_u32_e32 v70, s14, v64
	v_or_b32_e32 v70, v70, v86
	v_ashrrev_i32_e32 v71, 31, v70
	v_lshl_add_u64 v[70:71], v[70:71], 2, s[10:11]
	s_barrier
	global_load_dword v72, v[70:71], off
	global_load_dword v73, v[70:71], off offset:64
	global_load_dword v87, v[70:71], off offset:128
	global_load_dword v92, v[70:71], off offset:192
	v_and_b32_e32 v70, 48, v84
	v_or_b32_e32 v71, v64, v86
	v_lshl_or_b32 v64, v85, 8, v70
	v_mfma_f32_16x16x32_bf16 v[40:43], v[66:69], v[108:111], v[40:43]
	s_barrier
	v_mfma_f32_16x16x32_bf16 v[32:35], v[104:107], v[78:81], v[32:35]
	s_waitcnt vmcnt(3)
	v_fmamk_f32 v70, v72, 0x3a800000, v83
	s_waitcnt vmcnt(2)
	v_fmamk_f32 v72, v73, 0x3a800000, v83
	v_mul_f32_e32 v86, 0x4b800000, v70
	v_cmp_gt_f32_e32 vcc, s12, v70
	s_waitcnt vmcnt(1)
	v_fmamk_f32 v73, v87, 0x3a800000, v83
	v_mul_f32_e32 v87, 0x4b800000, v72
	v_cndmask_b32_e32 v70, v70, v86, vcc
	v_cmp_gt_f32_e64 s[4:5], s12, v72
	v_rsq_f32_e32 v70, v70
	s_waitcnt vmcnt(0)
	v_fmamk_f32 v85, v92, 0x3a800000, v83
	v_cndmask_b32_e64 v72, v72, v87, s[4:5]
	v_mul_f32_e32 v92, 0x4b800000, v73
	v_cmp_gt_f32_e64 s[6:7], s12, v73
	v_rsq_f32_e32 v72, v72
	v_mul_f32_e32 v93, 0x4b800000, v85
	v_cndmask_b32_e64 v73, v73, v92, s[6:7]
	v_cmp_gt_f32_e64 s[8:9], s12, v85
	v_rsq_f32_e32 v73, v73
	v_mfma_f32_16x16x32_bf16 v[28:31], v[100:103], v[78:81], v[28:31]
	v_cndmask_b32_e64 v85, v85, v93, s[8:9]
	v_mul_f32_e32 v86, 0x45800000, v70
	v_rsq_f32_e32 v85, v85
	v_mul_f32_e32 v87, 0x45800000, v72
	v_cndmask_b32_e32 v70, v70, v86, vcc
	v_mfma_f32_16x16x32_bf16 v[24:27], v[88:91], v[78:81], v[24:27]
	v_cndmask_b32_e64 v72, v72, v87, s[4:5]
	v_pk_mul_f32 v[42:43], v[42:43], v[70:71] op_sel_hi:[1,0]
	v_pk_mul_f32 v[40:41], v[40:41], v[70:71] op_sel_hi:[1,0]
	v_mfma_f32_16x16x32_bf16 v[20:23], v[66:69], v[78:81], v[20:23]
	v_mad_u64_u32 v[78:79], s[4:5], v71, s13, v[64:65]
	ds_write_b128 v78, v[40:43] offset:192
	v_mfma_f32_16x16x32_bf16 v[0:3], v[66:69], v[96:99], v[0:3]
	v_mul_f32_e64 v34, v34, v72
	v_mul_f32_e64 v35, v35, v72
	v_pk_mul_f32 v[32:33], v[32:33], v[72:73] op_sel_hi:[1,0]
	v_mul_f32_e32 v92, 0x45800000, v73
	v_mfma_f32_16x16x32_bf16 v[40:43], v[104:107], v[74:77], v[44:47]
	ds_write_b128 v78, v[32:35] offset:8448
	v_pk_mul_f32 v[30:31], v[30:31], v[72:73] op_sel_hi:[1,0]
	v_pk_mul_f32 v[28:29], v[28:29], v[72:73] op_sel_hi:[1,0]
	v_mfma_f32_16x16x32_bf16 v[32:35], v[100:103], v[74:77], v[48:51]
	v_mul_f32_e32 v93, 0x45800000, v85
	v_cndmask_b32_e64 v86, v73, v92, s[6:7]
	ds_write_b128 v78, v[28:31] offset:8512
	v_mfma_f32_16x16x32_bf16 v[28:31], v[88:91], v[74:77], v[36:39]
	v_cndmask_b32_e64 v92, v85, v93, s[8:9]
	v_pk_mul_f32 v[2:3], v[2:3], v[86:87] op_sel_hi:[1,0]
	v_pk_mul_f32 v[0:1], v[0:1], v[86:87] op_sel_hi:[1,0]
	v_mfma_f32_16x16x32_bf16 v[16:19], v[66:69], v[74:77], v[16:19]
	ds_write_b128 v78, v[0:3] offset:17088
	v_pk_mul_f32 v[2:3], v[42:43], v[92:93] op_sel_hi:[1,0]
	v_pk_mul_f32 v[0:1], v[40:41], v[92:93] op_sel_hi:[1,0]
	ds_write_b128 v78, v[0:3] offset:25344
	v_pk_mul_f32 v[2:3], v[34:35], v[92:93] op_sel_hi:[1,0]
	v_pk_mul_f32 v[0:1], v[32:33], v[92:93] op_sel_hi:[1,0]
	ds_write_b128 v78, v[0:3] offset:25408
	v_pk_mul_f32 v[2:3], v[30:31], v[92:93] op_sel_hi:[1,0]
	v_pk_mul_f32 v[0:1], v[28:29], v[92:93] op_sel_hi:[1,0]
	ds_write_b128 v78, v[0:3] offset:25472
	v_pk_mul_f32 v[2:3], v[18:19], v[92:93] op_sel_hi:[1,0]
	v_pk_mul_f32 v[0:1], v[16:17], v[92:93] op_sel_hi:[1,0]
	v_mfma_f32_16x16x32_bf16 v[60:63], v[104:107], v[108:111], v[60:63]
	ds_write_b128 v78, v[0:3] offset:25536
	v_lshlrev_b32_e32 v0, 3, v84
	v_and_b32_e32 v0, 0x78, v0
	v_mfma_f32_16x16x32_bf16 v[56:59], v[100:103], v[108:111], v[56:59]
	v_or_b32_e32 v2, s15, v0
	v_ashrrev_i32_e32 v3, 31, v2
	s_nop 1
	v_pk_mul_f32 v[62:63], v[62:63], v[70:71] op_sel_hi:[1,0]
	v_mfma_f32_16x16x32_bf16 v[52:55], v[88:91], v[108:111], v[52:55]
	v_mul_f32_e64 v60, v60, v70
	v_mul_f32_e64 v61, v61, v70
	v_pk_mul_f32 v[58:59], v[58:59], v[70:71] op_sel_hi:[1,0]
	v_pk_mul_f32 v[56:57], v[56:57], v[70:71] op_sel_hi:[1,0]
	v_mfma_f32_16x16x32_bf16 v[12:15], v[104:107], v[96:99], v[12:15]
	v_mul_f32_e64 v26, v26, v72
	v_mul_f32_e64 v27, v27, v72
	s_nop 0
	v_pk_mul_f32 v[54:55], v[54:55], v[70:71] op_sel_hi:[1,0]
	v_pk_mul_f32 v[52:53], v[52:53], v[70:71] op_sel_hi:[1,0]
	v_mfma_f32_16x16x32_bf16 v[8:11], v[100:103], v[96:99], v[8:11]
	v_mul_f32_e64 v24, v24, v72
	v_mul_f32_e64 v25, v25, v72
	v_pk_mul_f32 v[22:23], v[22:23], v[72:73] op_sel_hi:[1,0]
	v_pk_mul_f32 v[20:21], v[20:21], v[72:73] op_sel_hi:[1,0]
	v_mfma_f32_16x16x32_bf16 v[4:7], v[88:91], v[96:99], v[4:7]
	v_mul_f32_e64 v14, v14, v86
	v_mul_f32_e64 v15, v15, v86
	v_pk_mul_f32 v[12:13], v[12:13], v[86:87] op_sel_hi:[1,0]
	v_pk_mul_f32 v[10:11], v[10:11], v[86:87] op_sel_hi:[1,0]
	v_pk_mul_f32 v[8:9], v[8:9], v[86:87] op_sel_hi:[1,0]
	v_lshlrev_b32_e32 v0, 2, v0
	s_nop 1
	v_pk_mul_f32 v[6:7], v[6:7], v[86:87] op_sel_hi:[1,0]
	v_pk_mul_f32 v[4:5], v[4:5], v[86:87] op_sel_hi:[1,0]
	v_lshl_add_u64 v[2:3], v[2:3], 1, s[80:81]
	s_mov_b32 s4, 0
	ds_write_b128 v78, v[60:63]
	ds_write_b128 v78, v[56:59] offset:64
	ds_write_b128 v78, v[52:55] offset:128
	ds_write_b128 v78, v[24:27] offset:8576
	ds_write_b128 v78, v[20:23] offset:8640
	ds_write_b128 v78, v[12:15] offset:16896
	ds_write_b128 v78, v[8:11] offset:16960
	ds_write_b128 v78, v[4:7] offset:17024
	s_waitcnt lgkmcnt(0)
	s_barrier
